# removed redundant lgkmcnt waits inside GEMM MFMA blocks (LDS already drained before the phase barrier)
# speedup vs baseline: 1.0046x; 1.0046x over previous
.Lrx_skip_2:
	s_waitcnt vmcnt(24)
	s_waitcnt lgkmcnt(0)
	s_barrier
	s_setprio 1
	v_mfma_f32_16x16x32_bf16 v[126:129], v[130:133], v[186:189], v[126:129]
	v_mfma_f32_16x16x32_bf16 v[122:125], v[138:141], v[186:189], v[122:125]
	v_mfma_f32_16x16x32_bf16 v[110:113], v[130:133], v[220:223], v[110:113]
	v_mfma_f32_16x16x32_bf16 v[106:109], v[138:141], v[220:223], v[106:109]
	v_mfma_f32_16x16x32_bf16 v[94:97], v[130:133], v[228:231], v[94:97]
	v_mfma_f32_16x16x32_bf16 v[90:93], v[138:141], v[228:231], v[90:93]
	v_mfma_f32_16x16x32_bf16 v[78:81], v[130:133], v[236:239], v[78:81]
	v_mfma_f32_16x16x32_bf16 v[74:77], v[138:141], v[236:239], v[74:77]
	v_mfma_f32_16x16x32_bf16 v[126:129], v[134:137], v[190:193], v[126:129]
	v_mfma_f32_16x16x32_bf16 v[122:125], v[142:145], v[190:193], v[122:125]
	v_mfma_f32_16x16x32_bf16 v[110:113], v[134:137], v[224:227], v[110:113]
	v_mfma_f32_16x16x32_bf16 v[106:109], v[142:145], v[224:227], v[106:109]
	v_mfma_f32_16x16x32_bf16 v[94:97], v[134:137], v[232:235], v[94:97]
	v_mfma_f32_16x16x32_bf16 v[90:93], v[142:145], v[232:235], v[90:93]
	v_mfma_f32_16x16x32_bf16 v[78:81], v[134:137], v[240:243], v[78:81]
	v_mfma_f32_16x16x32_bf16 v[74:77], v[142:145], v[240:243], v[74:77]
	s_setprio 0
	s_setprio 1
	v_mfma_f32_16x16x32_bf16 v[118:121], v[146:149], v[186:189], v[118:121]
	v_mfma_f32_16x16x32_bf16 v[114:117], v[154:157], v[186:189], v[114:117]
	v_mfma_f32_16x16x32_bf16 v[102:105], v[146:149], v[220:223], v[102:105]
	v_mfma_f32_16x16x32_bf16 v[98:101], v[154:157], v[220:223], v[98:101]
	v_mfma_f32_16x16x32_bf16 v[86:89], v[146:149], v[228:231], v[86:89]
	v_mfma_f32_16x16x32_bf16 v[82:85], v[154:157], v[228:231], v[82:85]
	v_mfma_f32_16x16x32_bf16 v[70:73], v[146:149], v[236:239], v[70:73]
	v_mfma_f32_16x16x32_bf16 v[66:69], v[154:157], v[236:239], v[66:69]
	v_mfma_f32_16x16x32_bf16 v[118:121], v[150:153], v[190:193], v[118:121]
	v_mfma_f32_16x16x32_bf16 v[114:117], v[182:185], v[190:193], v[114:117]
	v_mfma_f32_16x16x32_bf16 v[102:105], v[150:153], v[224:227], v[102:105]
	v_mfma_f32_16x16x32_bf16 v[98:101], v[182:185], v[224:227], v[98:101]
	v_mfma_f32_16x16x32_bf16 v[86:89], v[150:153], v[232:235], v[86:89]
	v_mfma_f32_16x16x32_bf16 v[82:85], v[182:185], v[232:235], v[82:85]
	v_mfma_f32_16x16x32_bf16 v[70:73], v[150:153], v[240:243], v[70:73]
	v_mfma_f32_16x16x32_bf16 v[66:69], v[182:185], v[240:243], v[66:69]
	s_setprio 0
	s_barrier
	ds_read_b128 v[186:189], v216 offset:16384
	ds_read_b128 v[190:193], v216 offset:17408
	ds_read_b128 v[220:223], v216 offset:18432
	ds_read_b128 v[224:227], v216 offset:19456
	ds_read_b128 v[228:231], v216 offset:20480
	ds_read_b128 v[232:235], v216 offset:21504
	ds_read_b128 v[236:239], v216 offset:22528
	ds_read_b128 v[240:243], v216 offset:23552
	s_mov_b32 m0, s65
	s_nop 0
	global_load_lds_dwordx4 v209, s[62:63]
	s_nop 0
	s_mov_b32 m0, s66
	s_nop 0
	global_load_lds_dwordx4 v211, s[62:63]
	s_add_u32 s62, s62, s15
	s_addc_u32 s63, s63, 0
	s_mov_b32 m0, s67
	s_nop 0
	global_load_lds_dwordx4 v209, s[62:63]
	s_nop 0
	s_mov_b32 m0, s68
	s_nop 0
	global_load_lds_dwordx4 v211, s[62:63]
	s_nop 0
	s_mov_b32 m0, s64
	s_nop 0
	global_load_lds_dwordx4 v159, s[60:61]
	s_nop 0
	s_mov_b32 m0, s69
	s_nop 0
	global_load_lds_dwordx4 v210, s[60:61]
	s_cmp_lg_u32 s9, 0
	s_cbranch_scc1 .Lrx_skip_3
	s_waitcnt vmcnt(8)
.Lrx_skip_3:
	s_waitcnt vmcnt(24)
	s_waitcnt lgkmcnt(0)
	s_barrier
	s_setprio 1
	v_mfma_f32_16x16x32_bf16 v[62:65], v[130:133], v[186:189], v[62:65]
	v_mfma_f32_16x16x32_bf16 v[58:61], v[138:141], v[186:189], v[58:61]
	v_mfma_f32_16x16x32_bf16 v[46:49], v[130:133], v[220:223], v[46:49]
	v_mfma_f32_16x16x32_bf16 v[42:45], v[138:141], v[220:223], v[42:45]
	v_mfma_f32_16x16x32_bf16 v[30:33], v[130:133], v[228:231], v[30:33]
	v_mfma_f32_16x16x32_bf16 v[26:29], v[138:141], v[228:231], v[26:29]
	v_mfma_f32_16x16x32_bf16 v[14:17], v[130:133], v[236:239], v[14:17]
	v_mfma_f32_16x16x32_bf16 v[10:13], v[138:141], v[236:239], v[10:13]
	v_mfma_f32_16x16x32_bf16 v[62:65], v[134:137], v[190:193], v[62:65]
	v_mfma_f32_16x16x32_bf16 v[58:61], v[142:145], v[190:193], v[58:61]
	v_mfma_f32_16x16x32_bf16 v[46:49], v[134:137], v[224:227], v[46:49]
	v_mfma_f32_16x16x32_bf16 v[42:45], v[142:145], v[224:227], v[42:45]
	v_mfma_f32_16x16x32_bf16 v[30:33], v[134:137], v[232:235], v[30:33]
	v_mfma_f32_16x16x32_bf16 v[26:29], v[142:145], v[232:235], v[26:29]
	v_mfma_f32_16x16x32_bf16 v[14:17], v[134:137], v[240:243], v[14:17]
	v_mfma_f32_16x16x32_bf16 v[10:13], v[142:145], v[240:243], v[10:13]
	s_setprio 0
	s_setprio 1
	v_mfma_f32_16x16x32_bf16 v[54:57], v[146:149], v[186:189], v[54:57]
	v_mfma_f32_16x16x32_bf16 v[50:53], v[154:157], v[186:189], v[50:53]
	v_mfma_f32_16x16x32_bf16 v[38:41], v[146:149], v[220:223], v[38:41]
	v_mfma_f32_16x16x32_bf16 v[34:37], v[154:157], v[220:223], v[34:37]
	v_mfma_f32_16x16x32_bf16 v[22:25], v[146:149], v[228:231], v[22:25]
	v_mfma_f32_16x16x32_bf16 v[18:21], v[154:157], v[228:231], v[18:21]
	v_mfma_f32_16x16x32_bf16 v[6:9], v[146:149], v[236:239], v[6:9]
	v_mfma_f32_16x16x32_bf16 v[2:5], v[154:157], v[236:239], v[2:5]
	v_mfma_f32_16x16x32_bf16 v[54:57], v[150:153], v[190:193], v[54:57]
	v_mfma_f32_16x16x32_bf16 v[50:53], v[182:185], v[190:193], v[50:53]
	v_mfma_f32_16x16x32_bf16 v[38:41], v[150:153], v[224:227], v[38:41]
	v_mfma_f32_16x16x32_bf16 v[34:37], v[182:185], v[224:227], v[34:37]
	v_mfma_f32_16x16x32_bf16 v[22:25], v[150:153], v[232:235], v[22:25]
	v_mfma_f32_16x16x32_bf16 v[18:21], v[182:185], v[232:235], v[18:21]
	v_mfma_f32_16x16x32_bf16 v[6:9], v[150:153], v[240:243], v[6:9]
	v_mfma_f32_16x16x32_bf16 v[2:5], v[182:185], v[240:243], v[2:5]
	s_setprio 0
	s_barrier
	v_add_u32_e32 v142, 0x18000, v215
	v_add_u32_e32 v182, 0x1c000, v215
	ds_read_b128 v[130:133], v142
	ds_read_b128 v[134:137], v142 offset:1024
	ds_read_b128 v[138:141], v142 offset:2048
	ds_read_b128 v[142:145], v142 offset:3072
	ds_read_b128 v[146:149], v182
	ds_read_b128 v[150:153], v182 offset:1024
	ds_read_b128 v[154:157], v182 offset:2048
	ds_read_b128 v[182:185], v182 offset:3072
	ds_read_b128 v[186:189], v216 offset:32768
	ds_read_b128 v[190:193], v216 offset:33792
	ds_read_b128 v[220:223], v216 offset:34816
	ds_read_b128 v[224:227], v216 offset:35840
	ds_read_b128 v[228:231], v216 offset:36864
	ds_read_b128 v[232:235], v216 offset:37888
	ds_read_b128 v[236:239], v216 offset:38912
	ds_read_b128 v[240:243], v216 offset:39936
	s_add_u32 s18, s60, s15
	s_addc_u32 s19, s61, 0
	s_mov_b32 m0, s70
	s_nop 0
	global_load_lds_dwordx4 v159, s[18:19]
	s_nop 0
	s_mov_b32 m0, s71
	s_nop 0
	global_load_lds_dwordx4 v210, s[18:19]
	s_cmp_lg_u32 s9, 0
	s_cbranch_scc1 .Lrx_skip_4
	s_waitcnt vmcnt(8)
.Lrx_skip_4:
	s_waitcnt vmcnt(24)
	s_waitcnt lgkmcnt(0)
	s_barrier
	s_setprio 1
	v_mfma_f32_16x16x32_bf16 v[126:129], v[130:133], v[186:189], v[126:129]
	v_mfma_f32_16x16x32_bf16 v[122:125], v[138:141], v[186:189], v[122:125]
	v_mfma_f32_16x16x32_bf16 v[110:113], v[130:133], v[220:223], v[110:113]
	v_mfma_f32_16x16x32_bf16 v[106:109], v[138:141], v[220:223], v[106:109]
	v_mfma_f32_16x16x32_bf16 v[94:97], v[130:133], v[228:231], v[94:97]
	v_mfma_f32_16x16x32_bf16 v[90:93], v[138:141], v[228:231], v[90:93]
	v_mfma_f32_16x16x32_bf16 v[78:81], v[130:133], v[236:239], v[78:81]
	v_mfma_f32_16x16x32_bf16 v[74:77], v[138:141], v[236:239], v[74:77]
	v_mfma_f32_16x16x32_bf16 v[126:129], v[134:137], v[190:193], v[126:129]
	v_mfma_f32_16x16x32_bf16 v[122:125], v[142:145], v[190:193], v[122:125]
	v_mfma_f32_16x16x32_bf16 v[110:113], v[134:137], v[224:227], v[110:113]
	v_mfma_f32_16x16x32_bf16 v[106:109], v[142:145], v[224:227], v[106:109]
	v_mfma_f32_16x16x32_bf16 v[94:97], v[134:137], v[232:235], v[94:97]
	v_mfma_f32_16x16x32_bf16 v[90:93], v[142:145], v[232:235], v[90:93]
	v_mfma_f32_16x16x32_bf16 v[78:81], v[134:137], v[240:243], v[78:81]
	v_mfma_f32_16x16x32_bf16 v[74:77], v[142:145], v[240:243], v[74:77]
	s_setprio 0
	s_setprio 1
	v_mfma_f32_16x16x32_bf16 v[118:121], v[146:149], v[186:189], v[118:121]
	v_mfma_f32_16x16x32_bf16 v[114:117], v[154:157], v[186:189], v[114:117]
	v_mfma_f32_16x16x32_bf16 v[102:105], v[146:149], v[220:223], v[102:105]
	v_mfma_f32_16x16x32_bf16 v[98:101], v[154:157], v[220:223], v[98:101]
	v_mfma_f32_16x16x32_bf16 v[86:89], v[146:149], v[228:231], v[86:89]
	v_mfma_f32_16x16x32_bf16 v[82:85], v[154:157], v[228:231], v[82:85]
	v_mfma_f32_16x16x32_bf16 v[70:73], v[146:149], v[236:239], v[70:73]
	v_mfma_f32_16x16x32_bf16 v[66:69], v[154:157], v[236:239], v[66:69]
	v_mfma_f32_16x16x32_bf16 v[118:121], v[150:153], v[190:193], v[118:121]
	v_mfma_f32_16x16x32_bf16 v[114:117], v[182:185], v[190:193], v[114:117]
	v_mfma_f32_16x16x32_bf16 v[102:105], v[150:153], v[224:227], v[102:105]
	v_mfma_f32_16x16x32_bf16 v[98:101], v[182:185], v[224:227], v[98:101]
	v_mfma_f32_16x16x32_bf16 v[86:89], v[150:153], v[232:235], v[86:89]
	v_mfma_f32_16x16x32_bf16 v[82:85], v[182:185], v[232:235], v[82:85]
	v_mfma_f32_16x16x32_bf16 v[70:73], v[150:153], v[240:243], v[70:73]
	v_mfma_f32_16x16x32_bf16 v[66:69], v[182:185], v[240:243], v[66:69]
	s_setprio 0
	s_barrier
	ds_read_b128 v[186:189], v216 offset:49152
	ds_read_b128 v[190:193], v216 offset:50176
	ds_read_b128 v[220:223], v216 offset:51200
	ds_read_b128 v[224:227], v216 offset:52224
	ds_read_b128 v[228:231], v216 offset:53248
	ds_read_b128 v[232:235], v216 offset:54272
	ds_read_b128 v[236:239], v216 offset:55296
	ds_read_b128 v[240:243], v216 offset:56320
	s_mov_b32 m0, s74
	s_nop 0
	global_load_lds_dwordx4 v209, s[56:57]
	s_add_u32 s18, s62, 0x80
	s_mov_b32 m0, s75
	s_nop 0
	global_load_lds_dwordx4 v211, s[56:57]
	s_addc_u32 s19, s63, 0
	s_mov_b32 m0, s78
	s_nop 0
	global_load_lds_dwordx4 v209, s[18:19]
	s_nop 0
	s_mov_b32 m0, s79
	s_nop 0
	global_load_lds_dwordx4 v211, s[18:19]
	s_nop 0
	s_mov_b32 m0, s76
	s_nop 0
	global_load_lds_dwordx4 v159, s[34:35]
	s_nop 0
	s_mov_b32 m0, s77
	s_nop 0
	global_load_lds_dwordx4 v210, s[34:35]
	s_waitcnt vmcnt(8)
	s_waitcnt lgkmcnt(0)
	s_barrier
	s_setprio 1
	v_mfma_f32_16x16x32_bf16 v[62:65], v[130:133], v[186:189], v[62:65]
	v_mfma_f32_16x16x32_bf16 v[58:61], v[138:141], v[186:189], v[58:61]
	v_mfma_f32_16x16x32_bf16 v[46:49], v[130:133], v[220:223], v[46:49]
	v_mfma_f32_16x16x32_bf16 v[42:45], v[138:141], v[220:223], v[42:45]
	v_mfma_f32_16x16x32_bf16 v[30:33], v[130:133], v[228:231], v[30:33]
	v_mfma_f32_16x16x32_bf16 v[26:29], v[138:141], v[228:231], v[26:29]
	v_mfma_f32_16x16x32_bf16 v[14:17], v[130:133], v[236:239], v[14:17]
	v_mfma_f32_16x16x32_bf16 v[10:13], v[138:141], v[236:239], v[10:13]
	v_mfma_f32_16x16x32_bf16 v[62:65], v[134:137], v[190:193], v[62:65]
	v_mfma_f32_16x16x32_bf16 v[58:61], v[142:145], v[190:193], v[58:61]
	v_mfma_f32_16x16x32_bf16 v[46:49], v[134:137], v[224:227], v[46:49]
	v_mfma_f32_16x16x32_bf16 v[42:45], v[142:145], v[224:227], v[42:45]
	v_mfma_f32_16x16x32_bf16 v[30:33], v[134:137], v[232:235], v[30:33]
	v_mfma_f32_16x16x32_bf16 v[26:29], v[142:145], v[232:235], v[26:29]
	v_mfma_f32_16x16x32_bf16 v[14:17], v[134:137], v[240:243], v[14:17]
	v_mfma_f32_16x16x32_bf16 v[10:13], v[142:145], v[240:243], v[10:13]
	s_setprio 0
	s_setprio 1
	v_mfma_f32_16x16x32_bf16 v[54:57], v[146:149], v[186:189], v[54:57]
	v_mfma_f32_16x16x32_bf16 v[50:53], v[154:157], v[186:189], v[50:53]
	v_mfma_f32_16x16x32_bf16 v[38:41], v[146:149], v[220:223], v[38:41]
	v_mfma_f32_16x16x32_bf16 v[34:37], v[154:157], v[220:223], v[34:37]
	v_mfma_f32_16x16x32_bf16 v[22:25], v[146:149], v[228:231], v[22:25]
	v_mfma_f32_16x16x32_bf16 v[18:21], v[154:157], v[228:231], v[18:21]
	v_mfma_f32_16x16x32_bf16 v[6:9], v[146:149], v[236:239], v[6:9]
	v_mfma_f32_16x16x32_bf16 v[2:5], v[154:157], v[236:239], v[2:5]
	v_mfma_f32_16x16x32_bf16 v[54:57], v[150:153], v[190:193], v[54:57]
	v_mfma_f32_16x16x32_bf16 v[50:53], v[182:185], v[190:193], v[50:53]
	v_mfma_f32_16x16x32_bf16 v[38:41], v[150:153], v[224:227], v[38:41]
	v_mfma_f32_16x16x32_bf16 v[34:37], v[182:185], v[224:227], v[34:37]
	v_mfma_f32_16x16x32_bf16 v[22:25], v[150:153], v[232:235], v[22:25]
	v_mfma_f32_16x16x32_bf16 v[18:21], v[182:185], v[232:235], v[18:21]
	v_mfma_f32_16x16x32_bf16 v[6:9], v[150:153], v[240:243], v[6:9]
	v_mfma_f32_16x16x32_bf16 v[2:5], v[182:185], v[240:243], v[2:5]
	s_setprio 0
	s_barrier
	s_add_u32 vcc_lo, vcc_lo, 0x100
	s_addc_u32 vcc_hi, vcc_hi, 0
	s_add_u32 s31, s31, 0x100
	s_addc_u32 s22, s22, 0
	s_cmp_ge_u32 s23, s72
	s_mov_b32 s9, s23
	s_cbranch_scc0 .LBB0_52
	s_and_b64 vcc, exec, s[50:51]
	s_cbranch_vccz .LBB0_55
	s_barrier

.Lrx_skip_7:
	s_waitcnt vmcnt(24)
	s_waitcnt lgkmcnt(0)
	s_barrier
	s_setprio 1
	v_mfma_f32_16x16x32_bf16 v[126:129], v[130:133], v[214:217], v[126:129]
	v_mfma_f32_16x16x32_bf16 v[122:125], v[138:141], v[214:217], v[122:125]
	v_mfma_f32_16x16x32_bf16 v[110:113], v[130:133], v[222:225], v[110:113]
	v_mfma_f32_16x16x32_bf16 v[106:109], v[138:141], v[222:225], v[106:109]
	v_mfma_f32_16x16x32_bf16 v[94:97], v[130:133], v[230:233], v[94:97]
	v_mfma_f32_16x16x32_bf16 v[90:93], v[138:141], v[230:233], v[90:93]
	v_mfma_f32_16x16x32_bf16 v[78:81], v[130:133], v[238:241], v[78:81]
	v_mfma_f32_16x16x32_bf16 v[74:77], v[138:141], v[238:241], v[74:77]
	v_mfma_f32_16x16x32_bf16 v[126:129], v[134:137], v[218:221], v[126:129]
	v_mfma_f32_16x16x32_bf16 v[122:125], v[142:145], v[218:221], v[122:125]
	v_mfma_f32_16x16x32_bf16 v[110:113], v[134:137], v[226:229], v[110:113]
	v_mfma_f32_16x16x32_bf16 v[106:109], v[142:145], v[226:229], v[106:109]
	v_mfma_f32_16x16x32_bf16 v[94:97], v[134:137], v[234:237], v[94:97]
	v_mfma_f32_16x16x32_bf16 v[90:93], v[142:145], v[234:237], v[90:93]
	v_mfma_f32_16x16x32_bf16 v[78:81], v[134:137], v[242:245], v[78:81]
	v_mfma_f32_16x16x32_bf16 v[74:77], v[142:145], v[242:245], v[74:77]
	s_setprio 0
	s_setprio 1
	v_mfma_f32_16x16x32_bf16 v[118:121], v[182:185], v[214:217], v[118:121]
	v_mfma_f32_16x16x32_bf16 v[114:117], v[190:193], v[214:217], v[114:117]
	v_mfma_f32_16x16x32_bf16 v[102:105], v[182:185], v[222:225], v[102:105]
	v_mfma_f32_16x16x32_bf16 v[98:101], v[190:193], v[222:225], v[98:101]
	v_mfma_f32_16x16x32_bf16 v[86:89], v[182:185], v[230:233], v[86:89]
	v_mfma_f32_16x16x32_bf16 v[82:85], v[190:193], v[230:233], v[82:85]
	v_mfma_f32_16x16x32_bf16 v[70:73], v[182:185], v[238:241], v[70:73]
	v_mfma_f32_16x16x32_bf16 v[66:69], v[190:193], v[238:241], v[66:69]
	v_mfma_f32_16x16x32_bf16 v[118:121], v[186:189], v[218:221], v[118:121]
	v_mfma_f32_16x16x32_bf16 v[114:117], v[210:213], v[218:221], v[114:117]
	v_mfma_f32_16x16x32_bf16 v[102:105], v[186:189], v[226:229], v[102:105]
	v_mfma_f32_16x16x32_bf16 v[98:101], v[210:213], v[226:229], v[98:101]
	v_mfma_f32_16x16x32_bf16 v[86:89], v[186:189], v[234:237], v[86:89]
	v_mfma_f32_16x16x32_bf16 v[82:85], v[210:213], v[234:237], v[82:85]
	v_mfma_f32_16x16x32_bf16 v[70:73], v[186:189], v[242:245], v[70:73]
	v_mfma_f32_16x16x32_bf16 v[66:69], v[210:213], v[242:245], v[66:69]
	s_setprio 0
	s_barrier
	ds_read_b128 v[214:217], v154 offset:16384
	ds_read_b128 v[218:221], v154 offset:17408
	ds_read_b128 v[222:225], v154 offset:18432
	ds_read_b128 v[226:229], v154 offset:19456
	ds_read_b128 v[230:233], v154 offset:20480
	ds_read_b128 v[234:237], v154 offset:21504
	ds_read_b128 v[238:241], v154 offset:22528
	ds_read_b128 v[242:245], v154 offset:23552
	s_mov_b32 m0, s59
	s_nop 0
	global_load_lds_dwordx4 v148, s[38:39]
	s_add_u32 s8, s38, 0x40000
	s_mov_b32 m0, s60
	s_nop 0
	global_load_lds_dwordx4 v150, s[38:39]
	s_addc_u32 s9, s39, 0
	s_mov_b32 m0, s61
	s_nop 0
	global_load_lds_dwordx4 v148, s[8:9]
	s_nop 0
	s_mov_b32 m0, s62
	s_nop 0
	global_load_lds_dwordx4 v150, s[8:9]
	s_nop 0
	s_mov_b32 m0, s58
	s_nop 0
	global_load_lds_dwordx4 v0, s[56:57]
	s_nop 0
	s_mov_b32 m0, s63
	s_nop 0
	global_load_lds_dwordx4 v149, s[56:57]
	s_cmp_lg_u32 s18, 0
	s_cbranch_scc1 .Lrx_skip_8
	s_waitcnt vmcnt(8)
.Lrx_skip_8:
	s_waitcnt vmcnt(24)
	s_waitcnt lgkmcnt(0)
	s_barrier
	s_setprio 1
	v_mfma_f32_16x16x32_bf16 v[62:65], v[130:133], v[214:217], v[62:65]
	v_mfma_f32_16x16x32_bf16 v[58:61], v[138:141], v[214:217], v[58:61]
	v_mfma_f32_16x16x32_bf16 v[46:49], v[130:133], v[222:225], v[46:49]
	v_mfma_f32_16x16x32_bf16 v[42:45], v[138:141], v[222:225], v[42:45]
	v_mfma_f32_16x16x32_bf16 v[30:33], v[130:133], v[230:233], v[30:33]
	v_mfma_f32_16x16x32_bf16 v[26:29], v[138:141], v[230:233], v[26:29]
	v_mfma_f32_16x16x32_bf16 v[14:17], v[130:133], v[238:241], v[14:17]
	v_mfma_f32_16x16x32_bf16 v[10:13], v[138:141], v[238:241], v[10:13]
	v_mfma_f32_16x16x32_bf16 v[62:65], v[134:137], v[218:221], v[62:65]
	v_mfma_f32_16x16x32_bf16 v[58:61], v[142:145], v[218:221], v[58:61]
	v_mfma_f32_16x16x32_bf16 v[46:49], v[134:137], v[226:229], v[46:49]
	v_mfma_f32_16x16x32_bf16 v[42:45], v[142:145], v[226:229], v[42:45]
	v_mfma_f32_16x16x32_bf16 v[30:33], v[134:137], v[234:237], v[30:33]
	v_mfma_f32_16x16x32_bf16 v[26:29], v[142:145], v[234:237], v[26:29]
	v_mfma_f32_16x16x32_bf16 v[14:17], v[134:137], v[242:245], v[14:17]
	v_mfma_f32_16x16x32_bf16 v[10:13], v[142:145], v[242:245], v[10:13]
	s_setprio 0
	s_setprio 1
	v_mfma_f32_16x16x32_bf16 v[54:57], v[182:185], v[214:217], v[54:57]
	v_mfma_f32_16x16x32_bf16 v[50:53], v[190:193], v[214:217], v[50:53]
	v_mfma_f32_16x16x32_bf16 v[38:41], v[182:185], v[222:225], v[38:41]
	v_mfma_f32_16x16x32_bf16 v[34:37], v[190:193], v[222:225], v[34:37]
	v_mfma_f32_16x16x32_bf16 v[22:25], v[182:185], v[230:233], v[22:25]
	v_mfma_f32_16x16x32_bf16 v[18:21], v[190:193], v[230:233], v[18:21]
	v_mfma_f32_16x16x32_bf16 v[6:9], v[182:185], v[238:241], v[6:9]
	v_mfma_f32_16x16x32_bf16 v[2:5], v[190:193], v[238:241], v[2:5]
	v_mfma_f32_16x16x32_bf16 v[54:57], v[186:189], v[218:221], v[54:57]
	v_mfma_f32_16x16x32_bf16 v[50:53], v[210:213], v[218:221], v[50:53]
	v_mfma_f32_16x16x32_bf16 v[38:41], v[186:189], v[226:229], v[38:41]
	v_mfma_f32_16x16x32_bf16 v[34:37], v[210:213], v[226:229], v[34:37]
	v_mfma_f32_16x16x32_bf16 v[22:25], v[186:189], v[234:237], v[22:25]
	v_mfma_f32_16x16x32_bf16 v[18:21], v[210:213], v[234:237], v[18:21]
	v_mfma_f32_16x16x32_bf16 v[6:9], v[186:189], v[242:245], v[6:9]
	v_mfma_f32_16x16x32_bf16 v[2:5], v[210:213], v[242:245], v[2:5]
	s_setprio 0
	s_barrier
	v_add_u32_e32 v142, 0x18000, v153
	v_add_u32_e32 v146, 0x1c000, v153
	ds_read_b128 v[130:133], v142
	ds_read_b128 v[134:137], v142 offset:1024
	ds_read_b128 v[138:141], v142 offset:2048
	ds_read_b128 v[142:145], v142 offset:3072
	ds_read_b128 v[182:185], v146
	ds_read_b128 v[186:189], v146 offset:1024
	ds_read_b128 v[190:193], v146 offset:2048
	ds_read_b128 v[210:213], v146 offset:3072
	ds_read_b128 v[214:217], v154 offset:32768
	ds_read_b128 v[218:221], v154 offset:33792
	ds_read_b128 v[222:225], v154 offset:34816
	ds_read_b128 v[226:229], v154 offset:35840
	ds_read_b128 v[230:233], v154 offset:36864
	ds_read_b128 v[234:237], v154 offset:37888
	ds_read_b128 v[238:241], v154 offset:38912
	ds_read_b128 v[242:245], v154 offset:39936
	s_add_u32 s8, s56, 0x210000
	s_addc_u32 s9, s57, 0
	s_mov_b32 m0, s64
	s_nop 0
	global_load_lds_dwordx4 v0, s[8:9]
	s_nop 0
	s_mov_b32 m0, s65
	s_nop 0
	global_load_lds_dwordx4 v149, s[8:9]
	s_cmp_lg_u32 s18, 0
	s_cbranch_scc1 .Lrx_skip_9
	s_waitcnt vmcnt(8)
.Lrx_skip_9:
	s_waitcnt vmcnt(24)
	s_waitcnt lgkmcnt(0)
	s_barrier
	s_setprio 1
	v_mfma_f32_16x16x32_bf16 v[126:129], v[130:133], v[214:217], v[126:129]
	v_mfma_f32_16x16x32_bf16 v[122:125], v[138:141], v[214:217], v[122:125]
	v_mfma_f32_16x16x32_bf16 v[110:113], v[130:133], v[222:225], v[110:113]
	v_mfma_f32_16x16x32_bf16 v[106:109], v[138:141], v[222:225], v[106:109]
	v_mfma_f32_16x16x32_bf16 v[94:97], v[130:133], v[230:233], v[94:97]
	v_mfma_f32_16x16x32_bf16 v[90:93], v[138:141], v[230:233], v[90:93]
	v_mfma_f32_16x16x32_bf16 v[78:81], v[130:133], v[238:241], v[78:81]
	v_mfma_f32_16x16x32_bf16 v[74:77], v[138:141], v[238:241], v[74:77]
	v_mfma_f32_16x16x32_bf16 v[126:129], v[134:137], v[218:221], v[126:129]
	v_mfma_f32_16x16x32_bf16 v[122:125], v[142:145], v[218:221], v[122:125]
	v_mfma_f32_16x16x32_bf16 v[110:113], v[134:137], v[226:229], v[110:113]
	v_mfma_f32_16x16x32_bf16 v[106:109], v[142:145], v[226:229], v[106:109]
	v_mfma_f32_16x16x32_bf16 v[94:97], v[134:137], v[234:237], v[94:97]
	v_mfma_f32_16x16x32_bf16 v[90:93], v[142:145], v[234:237], v[90:93]
	v_mfma_f32_16x16x32_bf16 v[78:81], v[134:137], v[242:245], v[78:81]
	v_mfma_f32_16x16x32_bf16 v[74:77], v[142:145], v[242:245], v[74:77]
	s_setprio 0
	s_setprio 1
	v_mfma_f32_16x16x32_bf16 v[118:121], v[182:185], v[214:217], v[118:121]
	v_mfma_f32_16x16x32_bf16 v[114:117], v[190:193], v[214:217], v[114:117]
	v_mfma_f32_16x16x32_bf16 v[102:105], v[182:185], v[222:225], v[102:105]
	v_mfma_f32_16x16x32_bf16 v[98:101], v[190:193], v[222:225], v[98:101]
	v_mfma_f32_16x16x32_bf16 v[86:89], v[182:185], v[230:233], v[86:89]
	v_mfma_f32_16x16x32_bf16 v[82:85], v[190:193], v[230:233], v[82:85]
	v_mfma_f32_16x16x32_bf16 v[70:73], v[182:185], v[238:241], v[70:73]
	v_mfma_f32_16x16x32_bf16 v[66:69], v[190:193], v[238:241], v[66:69]
	v_mfma_f32_16x16x32_bf16 v[118:121], v[186:189], v[218:221], v[118:121]
	v_mfma_f32_16x16x32_bf16 v[114:117], v[210:213], v[218:221], v[114:117]
	v_mfma_f32_16x16x32_bf16 v[102:105], v[186:189], v[226:229], v[102:105]
	v_mfma_f32_16x16x32_bf16 v[98:101], v[210:213], v[226:229], v[98:101]
	v_mfma_f32_16x16x32_bf16 v[86:89], v[186:189], v[234:237], v[86:89]
	v_mfma_f32_16x16x32_bf16 v[82:85], v[210:213], v[234:237], v[82:85]
	v_mfma_f32_16x16x32_bf16 v[70:73], v[186:189], v[242:245], v[70:73]
	v_mfma_f32_16x16x32_bf16 v[66:69], v[210:213], v[242:245], v[66:69]
	s_setprio 0
	s_barrier
	ds_read_b128 v[214:217], v154 offset:49152
	ds_read_b128 v[218:221], v154 offset:50176
	ds_read_b128 v[222:225], v154 offset:51200
	ds_read_b128 v[226:229], v154 offset:52224
	ds_read_b128 v[230:233], v154 offset:53248
	ds_read_b128 v[234:237], v154 offset:54272
	ds_read_b128 v[238:241], v154 offset:55296
	ds_read_b128 v[242:245], v154 offset:56320
	s_mov_b32 m0, s66
	s_nop 0
	global_load_lds_dwordx4 v148, s[54:55]
	s_add_u32 s8, s38, 0x40080
	s_mov_b32 m0, s67
	s_nop 0
	global_load_lds_dwordx4 v150, s[54:55]
	s_addc_u32 s9, s39, 0
	s_mov_b32 m0, s70
	s_nop 0
	global_load_lds_dwordx4 v148, s[8:9]
	s_nop 0
	s_mov_b32 m0, s71
	s_nop 0
	global_load_lds_dwordx4 v150, s[8:9]
	s_nop 0
	s_mov_b32 m0, s68
	s_nop 0
	global_load_lds_dwordx4 v0, s[34:35]
	s_nop 0
	s_mov_b32 m0, s69
	s_nop 0
	global_load_lds_dwordx4 v149, s[34:35]
	s_waitcnt vmcnt(8)
	s_waitcnt lgkmcnt(0)
	s_barrier
	s_setprio 1
	v_mfma_f32_16x16x32_bf16 v[62:65], v[130:133], v[214:217], v[62:65]
	v_mfma_f32_16x16x32_bf16 v[58:61], v[138:141], v[214:217], v[58:61]
	v_mfma_f32_16x16x32_bf16 v[46:49], v[130:133], v[222:225], v[46:49]
	v_mfma_f32_16x16x32_bf16 v[42:45], v[138:141], v[222:225], v[42:45]
	v_mfma_f32_16x16x32_bf16 v[30:33], v[130:133], v[230:233], v[30:33]
	v_mfma_f32_16x16x32_bf16 v[26:29], v[138:141], v[230:233], v[26:29]
	v_mfma_f32_16x16x32_bf16 v[14:17], v[130:133], v[238:241], v[14:17]
	v_mfma_f32_16x16x32_bf16 v[10:13], v[138:141], v[238:241], v[10:13]
	v_mfma_f32_16x16x32_bf16 v[62:65], v[134:137], v[218:221], v[62:65]
	v_mfma_f32_16x16x32_bf16 v[58:61], v[142:145], v[218:221], v[58:61]
	v_mfma_f32_16x16x32_bf16 v[46:49], v[134:137], v[226:229], v[46:49]
	v_mfma_f32_16x16x32_bf16 v[42:45], v[142:145], v[226:229], v[42:45]
	v_mfma_f32_16x16x32_bf16 v[30:33], v[134:137], v[234:237], v[30:33]
	v_mfma_f32_16x16x32_bf16 v[26:29], v[142:145], v[234:237], v[26:29]
	v_mfma_f32_16x16x32_bf16 v[14:17], v[134:137], v[242:245], v[14:17]
	v_mfma_f32_16x16x32_bf16 v[10:13], v[142:145], v[242:245], v[10:13]
	s_setprio 0
	s_setprio 1
	v_mfma_f32_16x16x32_bf16 v[54:57], v[182:185], v[214:217], v[54:57]
	v_mfma_f32_16x16x32_bf16 v[50:53], v[190:193], v[214:217], v[50:53]
	v_mfma_f32_16x16x32_bf16 v[38:41], v[182:185], v[222:225], v[38:41]
	v_mfma_f32_16x16x32_bf16 v[34:37], v[190:193], v[222:225], v[34:37]
	v_mfma_f32_16x16x32_bf16 v[22:25], v[182:185], v[230:233], v[22:25]
	v_mfma_f32_16x16x32_bf16 v[18:21], v[190:193], v[230:233], v[18:21]
	v_mfma_f32_16x16x32_bf16 v[6:9], v[182:185], v[238:241], v[6:9]
	v_mfma_f32_16x16x32_bf16 v[2:5], v[190:193], v[238:241], v[2:5]
	v_mfma_f32_16x16x32_bf16 v[54:57], v[186:189], v[218:221], v[54:57]
	v_mfma_f32_16x16x32_bf16 v[50:53], v[210:213], v[218:221], v[50:53]
	v_mfma_f32_16x16x32_bf16 v[38:41], v[186:189], v[226:229], v[38:41]
	v_mfma_f32_16x16x32_bf16 v[34:37], v[210:213], v[226:229], v[34:37]
	v_mfma_f32_16x16x32_bf16 v[22:25], v[186:189], v[234:237], v[22:25]
	v_mfma_f32_16x16x32_bf16 v[18:21], v[210:213], v[234:237], v[18:21]
	v_mfma_f32_16x16x32_bf16 v[6:9], v[186:189], v[242:245], v[6:9]
	v_mfma_f32_16x16x32_bf16 v[2:5], v[210:213], v[242:245], v[2:5]
	s_setprio 0
	s_barrier
	s_add_i32 s91, s91, 2
	s_add_u32 s5, s5, 0x100
	s_addc_u32 s31, s31, 0
	s_add_u32 s6, s6, 0x100
	s_addc_u32 s7, s7, 0
	s_cmp_gt_u32 s91, 13
	s_cbranch_scc0 .LBB0_204
	s_and_b64 vcc, exec, s[44:45]
	s_cbranch_vccz .LBB0_207
	s_barrier

.Lrx_skip_12:
	s_waitcnt vmcnt(24)
	s_waitcnt lgkmcnt(0)
	s_barrier
	s_setprio 1
	v_mfma_f32_16x16x32_bf16 v[126:129], v[130:133], v[218:221], v[126:129]
	v_mfma_f32_16x16x32_bf16 v[122:125], v[152:155], v[218:221], v[122:125]
	v_mfma_f32_16x16x32_bf16 v[110:113], v[130:133], v[226:229], v[110:113]
	v_mfma_f32_16x16x32_bf16 v[106:109], v[152:155], v[226:229], v[106:109]
	v_mfma_f32_16x16x32_bf16 v[94:97], v[130:133], v[234:237], v[94:97]
	v_mfma_f32_16x16x32_bf16 v[90:93], v[152:155], v[234:237], v[90:93]
	v_mfma_f32_16x16x32_bf16 v[78:81], v[130:133], v[242:245], v[78:81]
	v_mfma_f32_16x16x32_bf16 v[74:77], v[152:155], v[242:245], v[74:77]
	v_mfma_f32_16x16x32_bf16 v[126:129], v[148:151], v[222:225], v[126:129]
	v_mfma_f32_16x16x32_bf16 v[122:125], v[182:185], v[222:225], v[122:125]
	v_mfma_f32_16x16x32_bf16 v[110:113], v[148:151], v[230:233], v[110:113]
	v_mfma_f32_16x16x32_bf16 v[106:109], v[182:185], v[230:233], v[106:109]
	v_mfma_f32_16x16x32_bf16 v[94:97], v[148:151], v[238:241], v[94:97]
	v_mfma_f32_16x16x32_bf16 v[90:93], v[182:185], v[238:241], v[90:93]
	v_mfma_f32_16x16x32_bf16 v[78:81], v[148:151], v[246:249], v[78:81]
	v_mfma_f32_16x16x32_bf16 v[74:77], v[182:185], v[246:249], v[74:77]
	s_setprio 0
	s_setprio 1
	v_mfma_f32_16x16x32_bf16 v[118:121], v[186:189], v[218:221], v[118:121]
	v_mfma_f32_16x16x32_bf16 v[114:117], v[210:213], v[218:221], v[114:117]
	v_mfma_f32_16x16x32_bf16 v[102:105], v[186:189], v[226:229], v[102:105]
	v_mfma_f32_16x16x32_bf16 v[98:101], v[210:213], v[226:229], v[98:101]
	v_mfma_f32_16x16x32_bf16 v[86:89], v[186:189], v[234:237], v[86:89]
	v_mfma_f32_16x16x32_bf16 v[82:85], v[210:213], v[234:237], v[82:85]
	v_mfma_f32_16x16x32_bf16 v[70:73], v[186:189], v[242:245], v[70:73]
	v_mfma_f32_16x16x32_bf16 v[66:69], v[210:213], v[242:245], v[66:69]
	v_mfma_f32_16x16x32_bf16 v[118:121], v[190:193], v[222:225], v[118:121]
	v_mfma_f32_16x16x32_bf16 v[114:117], v[214:217], v[222:225], v[114:117]
	v_mfma_f32_16x16x32_bf16 v[102:105], v[190:193], v[230:233], v[102:105]
	v_mfma_f32_16x16x32_bf16 v[98:101], v[214:217], v[230:233], v[98:101]
	v_mfma_f32_16x16x32_bf16 v[86:89], v[190:193], v[238:241], v[86:89]
	v_mfma_f32_16x16x32_bf16 v[82:85], v[214:217], v[238:241], v[82:85]
	v_mfma_f32_16x16x32_bf16 v[70:73], v[190:193], v[246:249], v[70:73]
	v_mfma_f32_16x16x32_bf16 v[66:69], v[214:217], v[246:249], v[66:69]
	s_setprio 0
	s_barrier
	ds_read_b128 v[218:221], v146 offset:16384
	ds_read_b128 v[222:225], v146 offset:17408
	ds_read_b128 v[226:229], v146 offset:18432
	ds_read_b128 v[230:233], v146 offset:19456
	ds_read_b128 v[234:237], v146 offset:20480
	ds_read_b128 v[238:241], v146 offset:21504
	ds_read_b128 v[242:245], v146 offset:22528
	ds_read_b128 v[246:249], v146 offset:23552
	s_mov_b32 m0, s56
	s_nop 0
	global_load_lds_dwordx4 v137, s[46:47]
	s_add_u32 s8, s46, 0x40000
	s_mov_b32 m0, s57
	s_nop 0
	global_load_lds_dwordx4 v139, s[46:47]
	s_addc_u32 s9, s47, 0
	s_mov_b32 m0, s58
	s_nop 0
	global_load_lds_dwordx4 v137, s[8:9]
	s_nop 0
	s_mov_b32 m0, s59
	s_nop 0
	global_load_lds_dwordx4 v139, s[8:9]
	s_nop 0
	s_mov_b32 m0, s39
	s_nop 0
	global_load_lds_dwordx4 v136, s[50:51]
	s_nop 0
	s_mov_b32 m0, s60
	s_nop 0
	global_load_lds_dwordx4 v138, s[50:51]
	s_cmp_lg_u32 s18, 0
	s_cbranch_scc1 .Lrx_skip_13
	s_waitcnt vmcnt(8)
.Lrx_skip_13:
	s_waitcnt vmcnt(24)
	s_waitcnt lgkmcnt(0)
	s_barrier
	s_setprio 1
	v_mfma_f32_16x16x32_bf16 v[62:65], v[130:133], v[218:221], v[62:65]
	v_mfma_f32_16x16x32_bf16 v[58:61], v[152:155], v[218:221], v[58:61]
	v_mfma_f32_16x16x32_bf16 v[46:49], v[130:133], v[226:229], v[46:49]
	v_mfma_f32_16x16x32_bf16 v[42:45], v[152:155], v[226:229], v[42:45]
	v_mfma_f32_16x16x32_bf16 v[30:33], v[130:133], v[234:237], v[30:33]
	v_mfma_f32_16x16x32_bf16 v[26:29], v[152:155], v[234:237], v[26:29]
	v_mfma_f32_16x16x32_bf16 v[14:17], v[130:133], v[242:245], v[14:17]
	v_mfma_f32_16x16x32_bf16 v[10:13], v[152:155], v[242:245], v[10:13]
	v_mfma_f32_16x16x32_bf16 v[62:65], v[148:151], v[222:225], v[62:65]
	v_mfma_f32_16x16x32_bf16 v[58:61], v[182:185], v[222:225], v[58:61]
	v_mfma_f32_16x16x32_bf16 v[46:49], v[148:151], v[230:233], v[46:49]
	v_mfma_f32_16x16x32_bf16 v[42:45], v[182:185], v[230:233], v[42:45]
	v_mfma_f32_16x16x32_bf16 v[30:33], v[148:151], v[238:241], v[30:33]
	v_mfma_f32_16x16x32_bf16 v[26:29], v[182:185], v[238:241], v[26:29]
	v_mfma_f32_16x16x32_bf16 v[14:17], v[148:151], v[246:249], v[14:17]
	v_mfma_f32_16x16x32_bf16 v[10:13], v[182:185], v[246:249], v[10:13]
	s_setprio 0
	s_setprio 1
	v_mfma_f32_16x16x32_bf16 v[54:57], v[186:189], v[218:221], v[54:57]
	v_mfma_f32_16x16x32_bf16 v[50:53], v[210:213], v[218:221], v[50:53]
	v_mfma_f32_16x16x32_bf16 v[38:41], v[186:189], v[226:229], v[38:41]
	v_mfma_f32_16x16x32_bf16 v[34:37], v[210:213], v[226:229], v[34:37]
	v_mfma_f32_16x16x32_bf16 v[22:25], v[186:189], v[234:237], v[22:25]
	v_mfma_f32_16x16x32_bf16 v[18:21], v[210:213], v[234:237], v[18:21]
	v_mfma_f32_16x16x32_bf16 v[6:9], v[186:189], v[242:245], v[6:9]
	v_mfma_f32_16x16x32_bf16 v[2:5], v[210:213], v[242:245], v[2:5]
	v_mfma_f32_16x16x32_bf16 v[54:57], v[190:193], v[222:225], v[54:57]
	v_mfma_f32_16x16x32_bf16 v[50:53], v[214:217], v[222:225], v[50:53]
	v_mfma_f32_16x16x32_bf16 v[38:41], v[190:193], v[230:233], v[38:41]
	v_mfma_f32_16x16x32_bf16 v[34:37], v[214:217], v[230:233], v[34:37]
	v_mfma_f32_16x16x32_bf16 v[22:25], v[190:193], v[238:241], v[22:25]
	v_mfma_f32_16x16x32_bf16 v[18:21], v[214:217], v[238:241], v[18:21]
	v_mfma_f32_16x16x32_bf16 v[6:9], v[190:193], v[246:249], v[6:9]
	v_mfma_f32_16x16x32_bf16 v[2:5], v[214:217], v[246:249], v[2:5]
	s_setprio 0
	s_barrier
	v_add_u32_e32 v147, 0x18000, v145
	ds_read_b128 v[130:133], v147
	ds_read_b128 v[148:151], v147 offset:1024
	ds_read_b128 v[152:155], v147 offset:2048
	ds_read_b128 v[182:185], v147 offset:3072
	v_add_u32_e32 v147, 0x1c000, v145
	ds_read_b128 v[186:189], v147
	ds_read_b128 v[190:193], v147 offset:1024
	ds_read_b128 v[210:213], v147 offset:2048
	ds_read_b128 v[214:217], v147 offset:3072
	ds_read_b128 v[218:221], v146 offset:32768
	ds_read_b128 v[222:225], v146 offset:33792
	ds_read_b128 v[226:229], v146 offset:34816
	ds_read_b128 v[230:233], v146 offset:35840
	ds_read_b128 v[234:237], v146 offset:36864
	ds_read_b128 v[238:241], v146 offset:37888
	ds_read_b128 v[242:245], v146 offset:38912
	ds_read_b128 v[246:249], v146 offset:39936
	s_add_u32 s8, s50, 0x40000
	s_addc_u32 s9, s51, 0
	s_mov_b32 m0, s61
	s_nop 0
	global_load_lds_dwordx4 v136, s[8:9]
	s_nop 0
	s_mov_b32 m0, s62
	s_nop 0
	global_load_lds_dwordx4 v138, s[8:9]
	s_cmp_lg_u32 s18, 0
	s_cbranch_scc1 .Lrx_skip_14
	s_waitcnt vmcnt(8)
.Lrx_skip_14:
	s_waitcnt vmcnt(24)
	s_waitcnt lgkmcnt(0)
	s_barrier
	s_setprio 1
	v_mfma_f32_16x16x32_bf16 v[126:129], v[130:133], v[218:221], v[126:129]
	v_mfma_f32_16x16x32_bf16 v[122:125], v[152:155], v[218:221], v[122:125]
	v_mfma_f32_16x16x32_bf16 v[110:113], v[130:133], v[226:229], v[110:113]
	v_mfma_f32_16x16x32_bf16 v[106:109], v[152:155], v[226:229], v[106:109]
	v_mfma_f32_16x16x32_bf16 v[94:97], v[130:133], v[234:237], v[94:97]
	v_mfma_f32_16x16x32_bf16 v[90:93], v[152:155], v[234:237], v[90:93]
	v_mfma_f32_16x16x32_bf16 v[78:81], v[130:133], v[242:245], v[78:81]
	v_mfma_f32_16x16x32_bf16 v[74:77], v[152:155], v[242:245], v[74:77]
	v_mfma_f32_16x16x32_bf16 v[126:129], v[148:151], v[222:225], v[126:129]
	v_mfma_f32_16x16x32_bf16 v[122:125], v[182:185], v[222:225], v[122:125]
	v_mfma_f32_16x16x32_bf16 v[110:113], v[148:151], v[230:233], v[110:113]
	v_mfma_f32_16x16x32_bf16 v[106:109], v[182:185], v[230:233], v[106:109]
	v_mfma_f32_16x16x32_bf16 v[94:97], v[148:151], v[238:241], v[94:97]
	v_mfma_f32_16x16x32_bf16 v[90:93], v[182:185], v[238:241], v[90:93]
	v_mfma_f32_16x16x32_bf16 v[78:81], v[148:151], v[246:249], v[78:81]
	v_mfma_f32_16x16x32_bf16 v[74:77], v[182:185], v[246:249], v[74:77]
	s_setprio 0
	s_setprio 1
	v_mfma_f32_16x16x32_bf16 v[118:121], v[186:189], v[218:221], v[118:121]
	v_mfma_f32_16x16x32_bf16 v[114:117], v[210:213], v[218:221], v[114:117]
	v_mfma_f32_16x16x32_bf16 v[102:105], v[186:189], v[226:229], v[102:105]
	v_mfma_f32_16x16x32_bf16 v[98:101], v[210:213], v[226:229], v[98:101]
	v_mfma_f32_16x16x32_bf16 v[86:89], v[186:189], v[234:237], v[86:89]
	v_mfma_f32_16x16x32_bf16 v[82:85], v[210:213], v[234:237], v[82:85]
	v_mfma_f32_16x16x32_bf16 v[70:73], v[186:189], v[242:245], v[70:73]
	v_mfma_f32_16x16x32_bf16 v[66:69], v[210:213], v[242:245], v[66:69]
	v_mfma_f32_16x16x32_bf16 v[118:121], v[190:193], v[222:225], v[118:121]
	v_mfma_f32_16x16x32_bf16 v[114:117], v[214:217], v[222:225], v[114:117]
	v_mfma_f32_16x16x32_bf16 v[102:105], v[190:193], v[230:233], v[102:105]
	v_mfma_f32_16x16x32_bf16 v[98:101], v[214:217], v[230:233], v[98:101]
	v_mfma_f32_16x16x32_bf16 v[86:89], v[190:193], v[238:241], v[86:89]
	v_mfma_f32_16x16x32_bf16 v[82:85], v[214:217], v[238:241], v[82:85]
	v_mfma_f32_16x16x32_bf16 v[70:73], v[190:193], v[246:249], v[70:73]
	v_mfma_f32_16x16x32_bf16 v[66:69], v[214:217], v[246:249], v[66:69]
	s_setprio 0
	s_barrier
	ds_read_b128 v[218:221], v146 offset:49152
	ds_read_b128 v[222:225], v146 offset:50176
	ds_read_b128 v[226:229], v146 offset:51200
	ds_read_b128 v[230:233], v146 offset:52224
	ds_read_b128 v[234:237], v146 offset:53248
	ds_read_b128 v[238:241], v146 offset:54272
	ds_read_b128 v[242:245], v146 offset:55296
	ds_read_b128 v[246:249], v146 offset:56320
	s_mov_b32 m0, s63
	s_nop 0
	global_load_lds_dwordx4 v137, s[48:49]
	s_add_u32 s8, s46, 0x40080
	s_mov_b32 m0, s64
	s_nop 0
	global_load_lds_dwordx4 v139, s[48:49]
	s_addc_u32 s9, s47, 0
	s_mov_b32 m0, s67
	s_nop 0
	global_load_lds_dwordx4 v137, s[8:9]
	s_nop 0
	s_mov_b32 m0, s68
	s_nop 0
	global_load_lds_dwordx4 v139, s[8:9]
	s_nop 0
	s_mov_b32 m0, s65
	s_nop 0
	global_load_lds_dwordx4 v136, s[42:43]
	s_nop 0
	s_mov_b32 m0, s66
	s_nop 0
	global_load_lds_dwordx4 v138, s[42:43]
	s_waitcnt vmcnt(8)
	s_waitcnt lgkmcnt(0)
	s_barrier
	s_setprio 1
	v_mfma_f32_16x16x32_bf16 v[62:65], v[130:133], v[218:221], v[62:65]
	v_mfma_f32_16x16x32_bf16 v[58:61], v[152:155], v[218:221], v[58:61]
	v_mfma_f32_16x16x32_bf16 v[46:49], v[130:133], v[226:229], v[46:49]
	v_mfma_f32_16x16x32_bf16 v[42:45], v[152:155], v[226:229], v[42:45]
	v_mfma_f32_16x16x32_bf16 v[30:33], v[130:133], v[234:237], v[30:33]
	v_mfma_f32_16x16x32_bf16 v[26:29], v[152:155], v[234:237], v[26:29]
	v_mfma_f32_16x16x32_bf16 v[14:17], v[130:133], v[242:245], v[14:17]
	v_mfma_f32_16x16x32_bf16 v[10:13], v[152:155], v[242:245], v[10:13]
	v_mfma_f32_16x16x32_bf16 v[62:65], v[148:151], v[222:225], v[62:65]
	v_mfma_f32_16x16x32_bf16 v[58:61], v[182:185], v[222:225], v[58:61]
	v_mfma_f32_16x16x32_bf16 v[46:49], v[148:151], v[230:233], v[46:49]
	v_mfma_f32_16x16x32_bf16 v[42:45], v[182:185], v[230:233], v[42:45]
	v_mfma_f32_16x16x32_bf16 v[30:33], v[148:151], v[238:241], v[30:33]
	v_mfma_f32_16x16x32_bf16 v[26:29], v[182:185], v[238:241], v[26:29]
	v_mfma_f32_16x16x32_bf16 v[14:17], v[148:151], v[246:249], v[14:17]
	v_mfma_f32_16x16x32_bf16 v[10:13], v[182:185], v[246:249], v[10:13]
	s_setprio 0
	s_setprio 1
	v_mfma_f32_16x16x32_bf16 v[54:57], v[186:189], v[218:221], v[54:57]
	v_mfma_f32_16x16x32_bf16 v[50:53], v[210:213], v[218:221], v[50:53]
	v_mfma_f32_16x16x32_bf16 v[38:41], v[186:189], v[226:229], v[38:41]
	v_mfma_f32_16x16x32_bf16 v[34:37], v[210:213], v[226:229], v[34:37]
	v_mfma_f32_16x16x32_bf16 v[22:25], v[186:189], v[234:237], v[22:25]
	v_mfma_f32_16x16x32_bf16 v[18:21], v[210:213], v[234:237], v[18:21]
	v_mfma_f32_16x16x32_bf16 v[6:9], v[186:189], v[242:245], v[6:9]
	v_mfma_f32_16x16x32_bf16 v[2:5], v[210:213], v[242:245], v[2:5]
	v_mfma_f32_16x16x32_bf16 v[54:57], v[190:193], v[222:225], v[54:57]
	v_mfma_f32_16x16x32_bf16 v[50:53], v[214:217], v[222:225], v[50:53]
	v_mfma_f32_16x16x32_bf16 v[38:41], v[190:193], v[230:233], v[38:41]
	v_mfma_f32_16x16x32_bf16 v[34:37], v[214:217], v[230:233], v[34:37]
	v_mfma_f32_16x16x32_bf16 v[22:25], v[190:193], v[238:241], v[22:25]
	v_mfma_f32_16x16x32_bf16 v[18:21], v[214:217], v[238:241], v[18:21]
	v_mfma_f32_16x16x32_bf16 v[6:9], v[190:193], v[246:249], v[6:9]
	v_mfma_f32_16x16x32_bf16 v[2:5], v[214:217], v[246:249], v[2:5]
	s_setprio 0
	s_barrier
	s_add_i32 s78, s78, 2
	s_add_u32 s76, s76, 0x100
	s_addc_u32 s77, s77, 0
	s_add_u32 s40, s40, 0x100
	s_addc_u32 s41, s41, 0
	s_cmp_gt_u32 s78, 13
	s_cbranch_scc0 .LBB0_373
	s_mov_b32 s96, 0x6dc9c883
	s_and_b64 vcc, exec, s[20:21]
	s_mov_b32 s97, 0x3fc45f30
	s_cbranch_vccz .LBB0_376
	s_barrier

.Lrx_skip_17:
	s_waitcnt vmcnt(24)
	s_waitcnt lgkmcnt(0)
	s_barrier
	s_setprio 1
	v_mfma_f32_16x16x32_bf16 v[126:129], v[144:147], v[218:221], v[126:129]
	v_mfma_f32_16x16x32_bf16 v[122:125], v[152:155], v[218:221], v[122:125]
	v_mfma_f32_16x16x32_bf16 v[110:113], v[144:147], v[226:229], v[110:113]
	v_mfma_f32_16x16x32_bf16 v[106:109], v[152:155], v[226:229], v[106:109]
	v_mfma_f32_16x16x32_bf16 v[94:97], v[144:147], v[234:237], v[94:97]
	v_mfma_f32_16x16x32_bf16 v[90:93], v[152:155], v[234:237], v[90:93]
	v_mfma_f32_16x16x32_bf16 v[78:81], v[144:147], v[242:245], v[78:81]
	v_mfma_f32_16x16x32_bf16 v[74:77], v[152:155], v[242:245], v[74:77]
	v_mfma_f32_16x16x32_bf16 v[126:129], v[148:151], v[222:225], v[126:129]
	v_mfma_f32_16x16x32_bf16 v[122:125], v[182:185], v[222:225], v[122:125]
	v_mfma_f32_16x16x32_bf16 v[110:113], v[148:151], v[230:233], v[110:113]
	v_mfma_f32_16x16x32_bf16 v[106:109], v[182:185], v[230:233], v[106:109]
	v_mfma_f32_16x16x32_bf16 v[94:97], v[148:151], v[238:241], v[94:97]
	v_mfma_f32_16x16x32_bf16 v[90:93], v[182:185], v[238:241], v[90:93]
	v_mfma_f32_16x16x32_bf16 v[78:81], v[148:151], v[246:249], v[78:81]
	v_mfma_f32_16x16x32_bf16 v[74:77], v[182:185], v[246:249], v[74:77]
	s_setprio 0
	s_setprio 1
	v_mfma_f32_16x16x32_bf16 v[118:121], v[186:189], v[218:221], v[118:121]
	v_mfma_f32_16x16x32_bf16 v[114:117], v[210:213], v[218:221], v[114:117]
	v_mfma_f32_16x16x32_bf16 v[102:105], v[186:189], v[226:229], v[102:105]
	v_mfma_f32_16x16x32_bf16 v[98:101], v[210:213], v[226:229], v[98:101]
	v_mfma_f32_16x16x32_bf16 v[86:89], v[186:189], v[234:237], v[86:89]
	v_mfma_f32_16x16x32_bf16 v[82:85], v[210:213], v[234:237], v[82:85]
	v_mfma_f32_16x16x32_bf16 v[70:73], v[186:189], v[242:245], v[70:73]
	v_mfma_f32_16x16x32_bf16 v[66:69], v[210:213], v[242:245], v[66:69]
	v_mfma_f32_16x16x32_bf16 v[118:121], v[190:193], v[222:225], v[118:121]
	v_mfma_f32_16x16x32_bf16 v[114:117], v[214:217], v[222:225], v[114:117]
	v_mfma_f32_16x16x32_bf16 v[102:105], v[190:193], v[230:233], v[102:105]
	v_mfma_f32_16x16x32_bf16 v[98:101], v[214:217], v[230:233], v[98:101]
	v_mfma_f32_16x16x32_bf16 v[86:89], v[190:193], v[238:241], v[86:89]
	v_mfma_f32_16x16x32_bf16 v[82:85], v[214:217], v[238:241], v[82:85]
	v_mfma_f32_16x16x32_bf16 v[70:73], v[190:193], v[246:249], v[70:73]
	v_mfma_f32_16x16x32_bf16 v[66:69], v[214:217], v[246:249], v[66:69]
	s_setprio 0
	s_barrier
	ds_read_b128 v[218:221], v143 offset:16384
	ds_read_b128 v[222:225], v143 offset:17408
	ds_read_b128 v[226:229], v143 offset:18432
	ds_read_b128 v[230:233], v143 offset:19456
	ds_read_b128 v[234:237], v143 offset:20480
	ds_read_b128 v[238:241], v143 offset:21504
	ds_read_b128 v[242:245], v143 offset:22528
	ds_read_b128 v[246:249], v143 offset:23552
	s_mov_b32 m0, s53
	s_nop 0
	global_load_lds_dwordx4 v137, s[46:47]
	s_add_u32 s8, s46, 0x40000
	s_mov_b32 m0, s54
	s_nop 0
	global_load_lds_dwordx4 v139, s[46:47]
	s_addc_u32 s9, s47, 0
	s_mov_b32 m0, s55
	s_nop 0
	global_load_lds_dwordx4 v137, s[8:9]
	s_nop 0
	s_mov_b32 m0, s56
	s_nop 0
	global_load_lds_dwordx4 v139, s[8:9]
	s_nop 0
	s_mov_b32 m0, s39
	s_nop 0
	global_load_lds_dwordx4 v136, s[50:51]
	s_nop 0
	s_mov_b32 m0, s57
	s_nop 0
	global_load_lds_dwordx4 v138, s[50:51]
	s_cmp_lg_u32 s18, 0
	s_cbranch_scc1 .Lrx_skip_18
	s_waitcnt vmcnt(8)
.Lrx_skip_18:
	s_waitcnt vmcnt(24)
	s_waitcnt lgkmcnt(0)
	s_barrier
	s_setprio 1
	v_mfma_f32_16x16x32_bf16 v[62:65], v[144:147], v[218:221], v[62:65]
	v_mfma_f32_16x16x32_bf16 v[58:61], v[152:155], v[218:221], v[58:61]
	v_mfma_f32_16x16x32_bf16 v[46:49], v[144:147], v[226:229], v[46:49]
	v_mfma_f32_16x16x32_bf16 v[42:45], v[152:155], v[226:229], v[42:45]
	v_mfma_f32_16x16x32_bf16 v[30:33], v[144:147], v[234:237], v[30:33]
	v_mfma_f32_16x16x32_bf16 v[26:29], v[152:155], v[234:237], v[26:29]
	v_mfma_f32_16x16x32_bf16 v[14:17], v[144:147], v[242:245], v[14:17]
	v_mfma_f32_16x16x32_bf16 v[10:13], v[152:155], v[242:245], v[10:13]
	v_mfma_f32_16x16x32_bf16 v[62:65], v[148:151], v[222:225], v[62:65]
	v_mfma_f32_16x16x32_bf16 v[58:61], v[182:185], v[222:225], v[58:61]
	v_mfma_f32_16x16x32_bf16 v[46:49], v[148:151], v[230:233], v[46:49]
	v_mfma_f32_16x16x32_bf16 v[42:45], v[182:185], v[230:233], v[42:45]
	v_mfma_f32_16x16x32_bf16 v[30:33], v[148:151], v[238:241], v[30:33]
	v_mfma_f32_16x16x32_bf16 v[26:29], v[182:185], v[238:241], v[26:29]
	v_mfma_f32_16x16x32_bf16 v[14:17], v[148:151], v[246:249], v[14:17]
	v_mfma_f32_16x16x32_bf16 v[10:13], v[182:185], v[246:249], v[10:13]
	s_setprio 0
	s_setprio 1
	v_mfma_f32_16x16x32_bf16 v[54:57], v[186:189], v[218:221], v[54:57]
	v_mfma_f32_16x16x32_bf16 v[50:53], v[210:213], v[218:221], v[50:53]
	v_mfma_f32_16x16x32_bf16 v[38:41], v[186:189], v[226:229], v[38:41]
	v_mfma_f32_16x16x32_bf16 v[34:37], v[210:213], v[226:229], v[34:37]
	v_mfma_f32_16x16x32_bf16 v[22:25], v[186:189], v[234:237], v[22:25]
	v_mfma_f32_16x16x32_bf16 v[18:21], v[210:213], v[234:237], v[18:21]
	v_mfma_f32_16x16x32_bf16 v[6:9], v[186:189], v[242:245], v[6:9]
	v_mfma_f32_16x16x32_bf16 v[2:5], v[210:213], v[242:245], v[2:5]
	v_mfma_f32_16x16x32_bf16 v[54:57], v[190:193], v[222:225], v[54:57]
	v_mfma_f32_16x16x32_bf16 v[50:53], v[214:217], v[222:225], v[50:53]
	v_mfma_f32_16x16x32_bf16 v[38:41], v[190:193], v[230:233], v[38:41]
	v_mfma_f32_16x16x32_bf16 v[34:37], v[214:217], v[230:233], v[34:37]
	v_mfma_f32_16x16x32_bf16 v[22:25], v[190:193], v[238:241], v[22:25]
	v_mfma_f32_16x16x32_bf16 v[18:21], v[214:217], v[238:241], v[18:21]
	v_mfma_f32_16x16x32_bf16 v[6:9], v[190:193], v[246:249], v[6:9]
	v_mfma_f32_16x16x32_bf16 v[2:5], v[214:217], v[246:249], v[2:5]
	s_setprio 0
	s_barrier
	v_add_u32_e32 v130, 0x18000, v142
	ds_read_b128 v[144:147], v130
	ds_read_b128 v[148:151], v130 offset:1024
	ds_read_b128 v[152:155], v130 offset:2048
	ds_read_b128 v[182:185], v130 offset:3072
	v_add_u32_e32 v130, 0x1c000, v142
	ds_read_b128 v[186:189], v130
	ds_read_b128 v[190:193], v130 offset:1024
	ds_read_b128 v[210:213], v130 offset:2048
	ds_read_b128 v[214:217], v130 offset:3072
	ds_read_b128 v[218:221], v143 offset:32768
	ds_read_b128 v[222:225], v143 offset:33792
	ds_read_b128 v[226:229], v143 offset:34816
	ds_read_b128 v[230:233], v143 offset:35840
	ds_read_b128 v[234:237], v143 offset:36864
	ds_read_b128 v[238:241], v143 offset:37888
	ds_read_b128 v[242:245], v143 offset:38912
	ds_read_b128 v[246:249], v143 offset:39936
	s_add_u32 s8, s50, 0x40000
	s_addc_u32 s9, s51, 0
	s_mov_b32 m0, s58
	s_nop 0
	global_load_lds_dwordx4 v136, s[8:9]
	s_nop 0
	s_mov_b32 m0, s59
	s_nop 0
	global_load_lds_dwordx4 v138, s[8:9]
	s_cmp_lg_u32 s18, 0
	s_cbranch_scc1 .Lrx_skip_19
	s_waitcnt vmcnt(8)
.Lrx_skip_19:
	s_waitcnt vmcnt(24)
	s_waitcnt lgkmcnt(0)
	s_barrier
	s_setprio 1
	v_mfma_f32_16x16x32_bf16 v[126:129], v[144:147], v[218:221], v[126:129]
	v_mfma_f32_16x16x32_bf16 v[122:125], v[152:155], v[218:221], v[122:125]
	v_mfma_f32_16x16x32_bf16 v[110:113], v[144:147], v[226:229], v[110:113]
	v_mfma_f32_16x16x32_bf16 v[106:109], v[152:155], v[226:229], v[106:109]
	v_mfma_f32_16x16x32_bf16 v[94:97], v[144:147], v[234:237], v[94:97]
	v_mfma_f32_16x16x32_bf16 v[90:93], v[152:155], v[234:237], v[90:93]
	v_mfma_f32_16x16x32_bf16 v[78:81], v[144:147], v[242:245], v[78:81]
	v_mfma_f32_16x16x32_bf16 v[74:77], v[152:155], v[242:245], v[74:77]
	v_mfma_f32_16x16x32_bf16 v[126:129], v[148:151], v[222:225], v[126:129]
	v_mfma_f32_16x16x32_bf16 v[122:125], v[182:185], v[222:225], v[122:125]
	v_mfma_f32_16x16x32_bf16 v[110:113], v[148:151], v[230:233], v[110:113]
	v_mfma_f32_16x16x32_bf16 v[106:109], v[182:185], v[230:233], v[106:109]
	v_mfma_f32_16x16x32_bf16 v[94:97], v[148:151], v[238:241], v[94:97]
	v_mfma_f32_16x16x32_bf16 v[90:93], v[182:185], v[238:241], v[90:93]
	v_mfma_f32_16x16x32_bf16 v[78:81], v[148:151], v[246:249], v[78:81]
	v_mfma_f32_16x16x32_bf16 v[74:77], v[182:185], v[246:249], v[74:77]
	s_setprio 0
	s_setprio 1
	v_mfma_f32_16x16x32_bf16 v[118:121], v[186:189], v[218:221], v[118:121]
	v_mfma_f32_16x16x32_bf16 v[114:117], v[210:213], v[218:221], v[114:117]
	v_mfma_f32_16x16x32_bf16 v[102:105], v[186:189], v[226:229], v[102:105]
	v_mfma_f32_16x16x32_bf16 v[98:101], v[210:213], v[226:229], v[98:101]
	v_mfma_f32_16x16x32_bf16 v[86:89], v[186:189], v[234:237], v[86:89]
	v_mfma_f32_16x16x32_bf16 v[82:85], v[210:213], v[234:237], v[82:85]
	v_mfma_f32_16x16x32_bf16 v[70:73], v[186:189], v[242:245], v[70:73]
	v_mfma_f32_16x16x32_bf16 v[66:69], v[210:213], v[242:245], v[66:69]
	v_mfma_f32_16x16x32_bf16 v[118:121], v[190:193], v[222:225], v[118:121]
	v_mfma_f32_16x16x32_bf16 v[114:117], v[214:217], v[222:225], v[114:117]
	v_mfma_f32_16x16x32_bf16 v[102:105], v[190:193], v[230:233], v[102:105]
	v_mfma_f32_16x16x32_bf16 v[98:101], v[214:217], v[230:233], v[98:101]
	v_mfma_f32_16x16x32_bf16 v[86:89], v[190:193], v[238:241], v[86:89]
	v_mfma_f32_16x16x32_bf16 v[82:85], v[214:217], v[238:241], v[82:85]
	v_mfma_f32_16x16x32_bf16 v[70:73], v[190:193], v[246:249], v[70:73]
	v_mfma_f32_16x16x32_bf16 v[66:69], v[214:217], v[246:249], v[66:69]
	s_setprio 0
	s_barrier
	ds_read_b128 v[218:221], v143 offset:49152
	ds_read_b128 v[222:225], v143 offset:50176
	ds_read_b128 v[226:229], v143 offset:51200
	ds_read_b128 v[230:233], v143 offset:52224
	ds_read_b128 v[234:237], v143 offset:53248
	ds_read_b128 v[238:241], v143 offset:54272
	ds_read_b128 v[242:245], v143 offset:55296
	ds_read_b128 v[246:249], v143 offset:56320
	s_mov_b32 m0, s60
	s_nop 0
	global_load_lds_dwordx4 v137, s[48:49]
	s_add_u32 s8, s46, 0x40080
	s_mov_b32 m0, s61
	s_nop 0
	global_load_lds_dwordx4 v139, s[48:49]
	s_addc_u32 s9, s47, 0
	s_mov_b32 m0, s64
	s_nop 0
	global_load_lds_dwordx4 v137, s[8:9]
	s_nop 0
	s_mov_b32 m0, s65
	s_nop 0
	global_load_lds_dwordx4 v139, s[8:9]
	s_nop 0
	s_mov_b32 m0, s62
	s_nop 0
	global_load_lds_dwordx4 v136, s[42:43]
	s_nop 0
	s_mov_b32 m0, s63
	s_nop 0
	global_load_lds_dwordx4 v138, s[42:43]
	s_waitcnt vmcnt(8)
	s_waitcnt lgkmcnt(0)
	s_barrier
	s_setprio 1
	v_mfma_f32_16x16x32_bf16 v[62:65], v[144:147], v[218:221], v[62:65]
	v_mfma_f32_16x16x32_bf16 v[58:61], v[152:155], v[218:221], v[58:61]
	v_mfma_f32_16x16x32_bf16 v[46:49], v[144:147], v[226:229], v[46:49]
	v_mfma_f32_16x16x32_bf16 v[42:45], v[152:155], v[226:229], v[42:45]
	v_mfma_f32_16x16x32_bf16 v[30:33], v[144:147], v[234:237], v[30:33]
	v_mfma_f32_16x16x32_bf16 v[26:29], v[152:155], v[234:237], v[26:29]
	v_mfma_f32_16x16x32_bf16 v[14:17], v[144:147], v[242:245], v[14:17]
	v_mfma_f32_16x16x32_bf16 v[10:13], v[152:155], v[242:245], v[10:13]
	v_mfma_f32_16x16x32_bf16 v[62:65], v[148:151], v[222:225], v[62:65]
	v_mfma_f32_16x16x32_bf16 v[58:61], v[182:185], v[222:225], v[58:61]
	v_mfma_f32_16x16x32_bf16 v[46:49], v[148:151], v[230:233], v[46:49]
	v_mfma_f32_16x16x32_bf16 v[42:45], v[182:185], v[230:233], v[42:45]
	v_mfma_f32_16x16x32_bf16 v[30:33], v[148:151], v[238:241], v[30:33]
	v_mfma_f32_16x16x32_bf16 v[26:29], v[182:185], v[238:241], v[26:29]
	v_mfma_f32_16x16x32_bf16 v[14:17], v[148:151], v[246:249], v[14:17]
	v_mfma_f32_16x16x32_bf16 v[10:13], v[182:185], v[246:249], v[10:13]
	s_setprio 0
	s_setprio 1
	v_mfma_f32_16x16x32_bf16 v[54:57], v[186:189], v[218:221], v[54:57]
	v_mfma_f32_16x16x32_bf16 v[50:53], v[210:213], v[218:221], v[50:53]
	v_mfma_f32_16x16x32_bf16 v[38:41], v[186:189], v[226:229], v[38:41]
	v_mfma_f32_16x16x32_bf16 v[34:37], v[210:213], v[226:229], v[34:37]
	v_mfma_f32_16x16x32_bf16 v[22:25], v[186:189], v[234:237], v[22:25]
	v_mfma_f32_16x16x32_bf16 v[18:21], v[210:213], v[234:237], v[18:21]
	v_mfma_f32_16x16x32_bf16 v[6:9], v[186:189], v[242:245], v[6:9]
	v_mfma_f32_16x16x32_bf16 v[2:5], v[210:213], v[242:245], v[2:5]
	v_mfma_f32_16x16x32_bf16 v[54:57], v[190:193], v[222:225], v[54:57]
	v_mfma_f32_16x16x32_bf16 v[50:53], v[214:217], v[222:225], v[50:53]
	v_mfma_f32_16x16x32_bf16 v[38:41], v[190:193], v[230:233], v[38:41]
	v_mfma_f32_16x16x32_bf16 v[34:37], v[214:217], v[230:233], v[34:37]
	v_mfma_f32_16x16x32_bf16 v[22:25], v[190:193], v[238:241], v[22:25]
	v_mfma_f32_16x16x32_bf16 v[18:21], v[214:217], v[238:241], v[18:21]
	v_mfma_f32_16x16x32_bf16 v[6:9], v[190:193], v[246:249], v[6:9]
	v_mfma_f32_16x16x32_bf16 v[2:5], v[214:217], v[246:249], v[2:5]
	s_setprio 0
	s_barrier
	s_add_i32 s75, s75, 2
	s_add_u32 s72, s72, 0x100
	s_addc_u32 s74, s74, 0
	s_add_u32 s40, s40, 0x100
	s_addc_u32 s41, s41, 0
	s_cmp_gt_u32 s75, 13
	s_cbranch_scc0 .LBB0_459
	s_and_b64 vcc, exec, s[22:23]
	s_cbranch_vccz .LBB0_462
	s_barrier

.Lrx_skip_22:
	s_waitcnt vmcnt(24)
	s_waitcnt lgkmcnt(0)
	s_barrier
	s_setprio 1
	v_mfma_f32_16x16x32_bf16 v[126:129], v[130:133], v[214:217], v[126:129]
	v_mfma_f32_16x16x32_bf16 v[122:125], v[148:151], v[214:217], v[122:125]
	v_mfma_f32_16x16x32_bf16 v[110:113], v[130:133], v[222:225], v[110:113]
	v_mfma_f32_16x16x32_bf16 v[106:109], v[148:151], v[222:225], v[106:109]
	v_mfma_f32_16x16x32_bf16 v[94:97], v[130:133], v[230:233], v[94:97]
	v_mfma_f32_16x16x32_bf16 v[90:93], v[148:151], v[230:233], v[90:93]
	v_mfma_f32_16x16x32_bf16 v[78:81], v[130:133], v[238:241], v[78:81]
	v_mfma_f32_16x16x32_bf16 v[74:77], v[148:151], v[238:241], v[74:77]
	v_mfma_f32_16x16x32_bf16 v[126:129], v[144:147], v[218:221], v[126:129]
	v_mfma_f32_16x16x32_bf16 v[122:125], v[152:155], v[218:221], v[122:125]
	v_mfma_f32_16x16x32_bf16 v[110:113], v[144:147], v[226:229], v[110:113]
	v_mfma_f32_16x16x32_bf16 v[106:109], v[152:155], v[226:229], v[106:109]
	v_mfma_f32_16x16x32_bf16 v[94:97], v[144:147], v[234:237], v[94:97]
	v_mfma_f32_16x16x32_bf16 v[90:93], v[152:155], v[234:237], v[90:93]
	v_mfma_f32_16x16x32_bf16 v[78:81], v[144:147], v[242:245], v[78:81]
	v_mfma_f32_16x16x32_bf16 v[74:77], v[152:155], v[242:245], v[74:77]
	s_setprio 0
	s_setprio 1
	v_mfma_f32_16x16x32_bf16 v[118:121], v[182:185], v[214:217], v[118:121]
	v_mfma_f32_16x16x32_bf16 v[114:117], v[190:193], v[214:217], v[114:117]
	v_mfma_f32_16x16x32_bf16 v[102:105], v[182:185], v[222:225], v[102:105]
	v_mfma_f32_16x16x32_bf16 v[98:101], v[190:193], v[222:225], v[98:101]
	v_mfma_f32_16x16x32_bf16 v[86:89], v[182:185], v[230:233], v[86:89]
	v_mfma_f32_16x16x32_bf16 v[82:85], v[190:193], v[230:233], v[82:85]
	v_mfma_f32_16x16x32_bf16 v[70:73], v[182:185], v[238:241], v[70:73]
	v_mfma_f32_16x16x32_bf16 v[66:69], v[190:193], v[238:241], v[66:69]
	v_mfma_f32_16x16x32_bf16 v[118:121], v[186:189], v[218:221], v[118:121]
	v_mfma_f32_16x16x32_bf16 v[114:117], v[210:213], v[218:221], v[114:117]
	v_mfma_f32_16x16x32_bf16 v[102:105], v[186:189], v[226:229], v[102:105]
	v_mfma_f32_16x16x32_bf16 v[98:101], v[210:213], v[226:229], v[98:101]
	v_mfma_f32_16x16x32_bf16 v[86:89], v[186:189], v[234:237], v[86:89]
	v_mfma_f32_16x16x32_bf16 v[82:85], v[210:213], v[234:237], v[82:85]
	v_mfma_f32_16x16x32_bf16 v[70:73], v[186:189], v[242:245], v[70:73]
	v_mfma_f32_16x16x32_bf16 v[66:69], v[210:213], v[242:245], v[66:69]
	s_setprio 0
	s_barrier
	ds_read_b128 v[214:217], v143 offset:16384
	ds_read_b128 v[218:221], v143 offset:17408
	ds_read_b128 v[222:225], v143 offset:18432
	ds_read_b128 v[226:229], v143 offset:19456
	ds_read_b128 v[230:233], v143 offset:20480
	ds_read_b128 v[234:237], v143 offset:21504
	ds_read_b128 v[238:241], v143 offset:22528
	ds_read_b128 v[242:245], v143 offset:23552
	s_mov_b32 m0, s59
	s_nop 0
	global_load_lds_dwordx4 v137, s[48:49]
	s_add_u32 s8, s48, 0x40000
	s_mov_b32 m0, s60
	s_nop 0
	global_load_lds_dwordx4 v139, s[48:49]
	s_addc_u32 s9, s49, 0
	s_mov_b32 m0, s61
	s_nop 0
	global_load_lds_dwordx4 v137, s[8:9]
	s_nop 0
	s_mov_b32 m0, s62
	s_nop 0
	global_load_lds_dwordx4 v139, s[8:9]
	s_nop 0
	s_mov_b32 m0, s58
	s_nop 0
	global_load_lds_dwordx4 v136, s[52:53]
	s_nop 0
	s_mov_b32 m0, s63
	s_nop 0
	global_load_lds_dwordx4 v138, s[52:53]
	s_cmp_lg_u32 s18, 0
	s_cbranch_scc1 .Lrx_skip_23
	s_waitcnt vmcnt(8)
.Lrx_skip_23:
	s_waitcnt vmcnt(24)
	s_waitcnt lgkmcnt(0)
	s_barrier
	s_setprio 1
	v_mfma_f32_16x16x32_bf16 v[62:65], v[130:133], v[214:217], v[62:65]
	v_mfma_f32_16x16x32_bf16 v[58:61], v[148:151], v[214:217], v[58:61]
	v_mfma_f32_16x16x32_bf16 v[46:49], v[130:133], v[222:225], v[46:49]
	v_mfma_f32_16x16x32_bf16 v[42:45], v[148:151], v[222:225], v[42:45]
	v_mfma_f32_16x16x32_bf16 v[30:33], v[130:133], v[230:233], v[30:33]
	v_mfma_f32_16x16x32_bf16 v[26:29], v[148:151], v[230:233], v[26:29]
	v_mfma_f32_16x16x32_bf16 v[14:17], v[130:133], v[238:241], v[14:17]
	v_mfma_f32_16x16x32_bf16 v[10:13], v[148:151], v[238:241], v[10:13]
	v_mfma_f32_16x16x32_bf16 v[62:65], v[144:147], v[218:221], v[62:65]
	v_mfma_f32_16x16x32_bf16 v[58:61], v[152:155], v[218:221], v[58:61]
	v_mfma_f32_16x16x32_bf16 v[46:49], v[144:147], v[226:229], v[46:49]
	v_mfma_f32_16x16x32_bf16 v[42:45], v[152:155], v[226:229], v[42:45]
	v_mfma_f32_16x16x32_bf16 v[30:33], v[144:147], v[234:237], v[30:33]
	v_mfma_f32_16x16x32_bf16 v[26:29], v[152:155], v[234:237], v[26:29]
	v_mfma_f32_16x16x32_bf16 v[14:17], v[144:147], v[242:245], v[14:17]
	v_mfma_f32_16x16x32_bf16 v[10:13], v[152:155], v[242:245], v[10:13]
	s_setprio 0
	s_setprio 1
	v_mfma_f32_16x16x32_bf16 v[54:57], v[182:185], v[214:217], v[54:57]
	v_mfma_f32_16x16x32_bf16 v[50:53], v[190:193], v[214:217], v[50:53]
	v_mfma_f32_16x16x32_bf16 v[38:41], v[182:185], v[222:225], v[38:41]
	v_mfma_f32_16x16x32_bf16 v[34:37], v[190:193], v[222:225], v[34:37]
	v_mfma_f32_16x16x32_bf16 v[22:25], v[182:185], v[230:233], v[22:25]
	v_mfma_f32_16x16x32_bf16 v[18:21], v[190:193], v[230:233], v[18:21]
	v_mfma_f32_16x16x32_bf16 v[6:9], v[182:185], v[238:241], v[6:9]
	v_mfma_f32_16x16x32_bf16 v[2:5], v[190:193], v[238:241], v[2:5]
	v_mfma_f32_16x16x32_bf16 v[54:57], v[186:189], v[218:221], v[54:57]
	v_mfma_f32_16x16x32_bf16 v[50:53], v[210:213], v[218:221], v[50:53]
	v_mfma_f32_16x16x32_bf16 v[38:41], v[186:189], v[226:229], v[38:41]
	v_mfma_f32_16x16x32_bf16 v[34:37], v[210:213], v[226:229], v[34:37]
	v_mfma_f32_16x16x32_bf16 v[22:25], v[186:189], v[234:237], v[22:25]
	v_mfma_f32_16x16x32_bf16 v[18:21], v[210:213], v[234:237], v[18:21]
	v_mfma_f32_16x16x32_bf16 v[6:9], v[186:189], v[242:245], v[6:9]
	v_mfma_f32_16x16x32_bf16 v[2:5], v[210:213], v[242:245], v[2:5]
	s_setprio 0
	s_barrier
	v_add_u32_e32 v0, 0x18000, v142
	ds_read_b128 v[130:133], v0
	ds_read_b128 v[144:147], v0 offset:1024
	ds_read_b128 v[148:151], v0 offset:2048
	ds_read_b128 v[152:155], v0 offset:3072
	v_add_u32_e32 v0, 0x1c000, v142
	ds_read_b128 v[182:185], v0
	ds_read_b128 v[186:189], v0 offset:1024
	ds_read_b128 v[190:193], v0 offset:2048
	ds_read_b128 v[210:213], v0 offset:3072
	ds_read_b128 v[214:217], v143 offset:32768
	ds_read_b128 v[218:221], v143 offset:33792
	ds_read_b128 v[222:225], v143 offset:34816
	ds_read_b128 v[226:229], v143 offset:35840
	ds_read_b128 v[230:233], v143 offset:36864
	ds_read_b128 v[234:237], v143 offset:37888
	ds_read_b128 v[238:241], v143 offset:38912
	ds_read_b128 v[242:245], v143 offset:39936
	s_add_u32 s8, s52, 0x40000
	s_addc_u32 s9, s53, 0
	s_mov_b32 m0, s64
	s_nop 0
	global_load_lds_dwordx4 v136, s[8:9]
	s_nop 0
	s_mov_b32 m0, s65
	s_nop 0
	global_load_lds_dwordx4 v138, s[8:9]
	s_cmp_lg_u32 s18, 0
	s_cbranch_scc1 .Lrx_skip_24
	s_waitcnt vmcnt(8)
.Lrx_skip_24:
	s_waitcnt vmcnt(24)
	s_waitcnt lgkmcnt(0)
	s_barrier
	s_setprio 1
	v_mfma_f32_16x16x32_bf16 v[126:129], v[130:133], v[214:217], v[126:129]
	v_mfma_f32_16x16x32_bf16 v[122:125], v[148:151], v[214:217], v[122:125]
	v_mfma_f32_16x16x32_bf16 v[110:113], v[130:133], v[222:225], v[110:113]
	v_mfma_f32_16x16x32_bf16 v[106:109], v[148:151], v[222:225], v[106:109]
	v_mfma_f32_16x16x32_bf16 v[94:97], v[130:133], v[230:233], v[94:97]
	v_mfma_f32_16x16x32_bf16 v[90:93], v[148:151], v[230:233], v[90:93]
	v_mfma_f32_16x16x32_bf16 v[78:81], v[130:133], v[238:241], v[78:81]
	v_mfma_f32_16x16x32_bf16 v[74:77], v[148:151], v[238:241], v[74:77]
	v_mfma_f32_16x16x32_bf16 v[126:129], v[144:147], v[218:221], v[126:129]
	v_mfma_f32_16x16x32_bf16 v[122:125], v[152:155], v[218:221], v[122:125]
	v_mfma_f32_16x16x32_bf16 v[110:113], v[144:147], v[226:229], v[110:113]
	v_mfma_f32_16x16x32_bf16 v[106:109], v[152:155], v[226:229], v[106:109]
	v_mfma_f32_16x16x32_bf16 v[94:97], v[144:147], v[234:237], v[94:97]
	v_mfma_f32_16x16x32_bf16 v[90:93], v[152:155], v[234:237], v[90:93]
	v_mfma_f32_16x16x32_bf16 v[78:81], v[144:147], v[242:245], v[78:81]
	v_mfma_f32_16x16x32_bf16 v[74:77], v[152:155], v[242:245], v[74:77]
	s_setprio 0
	s_setprio 1
	v_mfma_f32_16x16x32_bf16 v[118:121], v[182:185], v[214:217], v[118:121]
	v_mfma_f32_16x16x32_bf16 v[114:117], v[190:193], v[214:217], v[114:117]
	v_mfma_f32_16x16x32_bf16 v[102:105], v[182:185], v[222:225], v[102:105]
	v_mfma_f32_16x16x32_bf16 v[98:101], v[190:193], v[222:225], v[98:101]
	v_mfma_f32_16x16x32_bf16 v[86:89], v[182:185], v[230:233], v[86:89]
	v_mfma_f32_16x16x32_bf16 v[82:85], v[190:193], v[230:233], v[82:85]
	v_mfma_f32_16x16x32_bf16 v[70:73], v[182:185], v[238:241], v[70:73]
	v_mfma_f32_16x16x32_bf16 v[66:69], v[190:193], v[238:241], v[66:69]
	v_mfma_f32_16x16x32_bf16 v[118:121], v[186:189], v[218:221], v[118:121]
	v_mfma_f32_16x16x32_bf16 v[114:117], v[210:213], v[218:221], v[114:117]
	v_mfma_f32_16x16x32_bf16 v[102:105], v[186:189], v[226:229], v[102:105]
	v_mfma_f32_16x16x32_bf16 v[98:101], v[210:213], v[226:229], v[98:101]
	v_mfma_f32_16x16x32_bf16 v[86:89], v[186:189], v[234:237], v[86:89]
	v_mfma_f32_16x16x32_bf16 v[82:85], v[210:213], v[234:237], v[82:85]
	v_mfma_f32_16x16x32_bf16 v[70:73], v[186:189], v[242:245], v[70:73]
	v_mfma_f32_16x16x32_bf16 v[66:69], v[210:213], v[242:245], v[66:69]
	s_setprio 0
	s_barrier
	ds_read_b128 v[214:217], v143 offset:49152
	ds_read_b128 v[218:221], v143 offset:50176
	ds_read_b128 v[222:225], v143 offset:51200
	ds_read_b128 v[226:229], v143 offset:52224
	ds_read_b128 v[230:233], v143 offset:53248
	ds_read_b128 v[234:237], v143 offset:54272
	ds_read_b128 v[238:241], v143 offset:55296
	ds_read_b128 v[242:245], v143 offset:56320
	s_mov_b32 m0, s67
	s_nop 0
	global_load_lds_dwordx4 v137, s[50:51]
	s_add_u32 s8, s48, 0x40080
	s_mov_b32 m0, s68
	s_nop 0
	global_load_lds_dwordx4 v139, s[50:51]
	s_addc_u32 s9, s49, 0
	s_mov_b32 m0, s71
	s_nop 0
	global_load_lds_dwordx4 v137, s[8:9]
	s_nop 0
	s_mov_b32 m0, s72
	s_nop 0
	global_load_lds_dwordx4 v139, s[8:9]
	s_nop 0
	s_mov_b32 m0, s69
	s_nop 0
	global_load_lds_dwordx4 v136, s[44:45]
	s_nop 0
	s_mov_b32 m0, s70
	s_nop 0
	global_load_lds_dwordx4 v138, s[44:45]
	s_waitcnt vmcnt(8)
	s_waitcnt lgkmcnt(0)
	s_barrier
	s_setprio 1
	v_mfma_f32_16x16x32_bf16 v[62:65], v[130:133], v[214:217], v[62:65]
	v_mfma_f32_16x16x32_bf16 v[58:61], v[148:151], v[214:217], v[58:61]
	v_mfma_f32_16x16x32_bf16 v[46:49], v[130:133], v[222:225], v[46:49]
	v_mfma_f32_16x16x32_bf16 v[42:45], v[148:151], v[222:225], v[42:45]
	v_mfma_f32_16x16x32_bf16 v[30:33], v[130:133], v[230:233], v[30:33]
	v_mfma_f32_16x16x32_bf16 v[26:29], v[148:151], v[230:233], v[26:29]
	v_mfma_f32_16x16x32_bf16 v[14:17], v[130:133], v[238:241], v[14:17]
	v_mfma_f32_16x16x32_bf16 v[10:13], v[148:151], v[238:241], v[10:13]
	v_mfma_f32_16x16x32_bf16 v[62:65], v[144:147], v[218:221], v[62:65]
	v_mfma_f32_16x16x32_bf16 v[58:61], v[152:155], v[218:221], v[58:61]
	v_mfma_f32_16x16x32_bf16 v[46:49], v[144:147], v[226:229], v[46:49]
	v_mfma_f32_16x16x32_bf16 v[42:45], v[152:155], v[226:229], v[42:45]
	v_mfma_f32_16x16x32_bf16 v[30:33], v[144:147], v[234:237], v[30:33]
	v_mfma_f32_16x16x32_bf16 v[26:29], v[152:155], v[234:237], v[26:29]
	v_mfma_f32_16x16x32_bf16 v[14:17], v[144:147], v[242:245], v[14:17]
	v_mfma_f32_16x16x32_bf16 v[10:13], v[152:155], v[242:245], v[10:13]
	s_setprio 0
	s_setprio 1
	v_mfma_f32_16x16x32_bf16 v[54:57], v[182:185], v[214:217], v[54:57]
	v_mfma_f32_16x16x32_bf16 v[50:53], v[190:193], v[214:217], v[50:53]
	v_mfma_f32_16x16x32_bf16 v[38:41], v[182:185], v[222:225], v[38:41]
	v_mfma_f32_16x16x32_bf16 v[34:37], v[190:193], v[222:225], v[34:37]
	v_mfma_f32_16x16x32_bf16 v[22:25], v[182:185], v[230:233], v[22:25]
	v_mfma_f32_16x16x32_bf16 v[18:21], v[190:193], v[230:233], v[18:21]
	v_mfma_f32_16x16x32_bf16 v[6:9], v[182:185], v[238:241], v[6:9]
	v_mfma_f32_16x16x32_bf16 v[2:5], v[190:193], v[238:241], v[2:5]
	v_mfma_f32_16x16x32_bf16 v[54:57], v[186:189], v[218:221], v[54:57]
	v_mfma_f32_16x16x32_bf16 v[50:53], v[210:213], v[218:221], v[50:53]
	v_mfma_f32_16x16x32_bf16 v[38:41], v[186:189], v[226:229], v[38:41]
	v_mfma_f32_16x16x32_bf16 v[34:37], v[210:213], v[226:229], v[34:37]
	v_mfma_f32_16x16x32_bf16 v[22:25], v[186:189], v[234:237], v[22:25]
	v_mfma_f32_16x16x32_bf16 v[18:21], v[210:213], v[234:237], v[18:21]
	v_mfma_f32_16x16x32_bf16 v[6:9], v[186:189], v[242:245], v[6:9]
	v_mfma_f32_16x16x32_bf16 v[2:5], v[210:213], v[242:245], v[2:5]
	s_setprio 0
	s_barrier
	s_add_i32 s79, s79, 2
	s_add_u32 s35, s35, 0x100
	s_addc_u32 s78, s78, 0
	s_add_u32 s42, s42, 0x100
	s_addc_u32 s43, s43, 0
	s_cmp_gt_u32 s79, 13
	s_cbranch_scc0 .LBB0_489
	s_and_b64 vcc, exec, s[22:23]
	s_cbranch_vccz .LBB0_492
	s_barrier

.Lrx_skip_27:
	s_waitcnt vmcnt(16)
	s_waitcnt lgkmcnt(0)
	s_barrier
	s_setprio 1
	v_mfma_f32_16x16x32_bf16 v[122:125], v[140:143], v[214:217], v[122:125]
	v_mfma_f32_16x16x32_bf16 v[114:117], v[148:151], v[214:217], v[114:117]
	v_mfma_f32_16x16x32_bf16 v[106:109], v[140:143], v[222:225], v[106:109]
	v_mfma_f32_16x16x32_bf16 v[98:101], v[148:151], v[222:225], v[98:101]
	v_mfma_f32_16x16x32_bf16 v[90:93], v[140:143], v[230:233], v[90:93]
	v_mfma_f32_16x16x32_bf16 v[82:85], v[148:151], v[230:233], v[82:85]
	v_mfma_f32_16x16x32_bf16 v[74:77], v[140:143], v[238:241], v[74:77]
	v_mfma_f32_16x16x32_bf16 v[66:69], v[148:151], v[238:241], v[66:69]
	v_mfma_f32_16x16x32_bf16 v[122:125], v[144:147], v[218:221], v[122:125]
	v_mfma_f32_16x16x32_bf16 v[114:117], v[152:155], v[218:221], v[114:117]
	v_mfma_f32_16x16x32_bf16 v[106:109], v[144:147], v[226:229], v[106:109]
	v_mfma_f32_16x16x32_bf16 v[98:101], v[152:155], v[226:229], v[98:101]
	v_mfma_f32_16x16x32_bf16 v[90:93], v[144:147], v[234:237], v[90:93]
	v_mfma_f32_16x16x32_bf16 v[82:85], v[152:155], v[234:237], v[82:85]
	v_mfma_f32_16x16x32_bf16 v[74:77], v[144:147], v[242:245], v[74:77]
	v_mfma_f32_16x16x32_bf16 v[66:69], v[152:155], v[242:245], v[66:69]
	s_setprio 0
	s_setprio 1
	v_mfma_f32_16x16x32_bf16 v[126:129], v[182:185], v[214:217], v[126:129]
	v_mfma_f32_16x16x32_bf16 v[118:121], v[190:193], v[214:217], v[118:121]
	v_mfma_f32_16x16x32_bf16 v[110:113], v[182:185], v[222:225], v[110:113]
	v_mfma_f32_16x16x32_bf16 v[102:105], v[190:193], v[222:225], v[102:105]
	v_mfma_f32_16x16x32_bf16 v[94:97], v[182:185], v[230:233], v[94:97]
	v_mfma_f32_16x16x32_bf16 v[86:89], v[190:193], v[230:233], v[86:89]
	v_mfma_f32_16x16x32_bf16 v[78:81], v[182:185], v[238:241], v[78:81]
	v_mfma_f32_16x16x32_bf16 v[70:73], v[190:193], v[238:241], v[70:73]
	v_mfma_f32_16x16x32_bf16 v[126:129], v[186:189], v[218:221], v[126:129]
	v_mfma_f32_16x16x32_bf16 v[118:121], v[210:213], v[218:221], v[118:121]
	v_mfma_f32_16x16x32_bf16 v[110:113], v[186:189], v[226:229], v[110:113]
	v_mfma_f32_16x16x32_bf16 v[102:105], v[210:213], v[226:229], v[102:105]
	v_mfma_f32_16x16x32_bf16 v[94:97], v[186:189], v[234:237], v[94:97]
	v_mfma_f32_16x16x32_bf16 v[86:89], v[210:213], v[234:237], v[86:89]
	v_mfma_f32_16x16x32_bf16 v[78:81], v[186:189], v[242:245], v[78:81]
	v_mfma_f32_16x16x32_bf16 v[70:73], v[210:213], v[242:245], v[70:73]
	s_setprio 0
	s_barrier
	ds_read_b128 v[214:217], v139 offset:16384
	ds_read_b128 v[218:221], v139 offset:17408
	ds_read_b128 v[222:225], v139 offset:18432
	ds_read_b128 v[226:229], v139 offset:19456
	ds_read_b128 v[230:233], v139 offset:20480
	ds_read_b128 v[234:237], v139 offset:21504
	ds_read_b128 v[238:241], v139 offset:22528
	ds_read_b128 v[242:245], v139 offset:23552
	s_mov_b32 m0, s52
	s_nop 0
	global_load_lds_dwordx4 v132, s[44:45]
	s_add_u32 s8, s44, 0x40000
	s_mov_b32 m0, s53
	s_nop 0
	global_load_lds_dwordx4 v134, s[44:45]
	s_addc_u32 s9, s45, 0
	s_mov_b32 m0, s54
	s_nop 0
	global_load_lds_dwordx4 v132, s[8:9]
	s_nop 0
	s_mov_b32 m0, s55
	s_nop 0
	global_load_lds_dwordx4 v134, s[8:9]
	s_nop 0
	s_mov_b32 m0, s35
	s_nop 0
	global_load_lds_dwordx4 v0, s[48:49]
	s_nop 0
	s_mov_b32 m0, s56
	s_nop 0
	global_load_lds_dwordx4 v133, s[48:49]
	s_cmp_lg_u32 s18, 0
	s_cbranch_scc1 .Lrx_skip_28
	s_waitcnt vmcnt(8)
.Lrx_skip_28:
	s_waitcnt vmcnt(16)
	s_waitcnt lgkmcnt(0)
	s_barrier
	s_setprio 1
	v_mfma_f32_16x16x32_bf16 v[58:61], v[140:143], v[214:217], v[58:61]
	v_mfma_f32_16x16x32_bf16 v[50:53], v[148:151], v[214:217], v[50:53]
	v_mfma_f32_16x16x32_bf16 v[42:45], v[140:143], v[222:225], v[42:45]
	v_mfma_f32_16x16x32_bf16 v[34:37], v[148:151], v[222:225], v[34:37]
	v_mfma_f32_16x16x32_bf16 v[26:29], v[140:143], v[230:233], v[26:29]
	v_mfma_f32_16x16x32_bf16 v[18:21], v[148:151], v[230:233], v[18:21]
	v_mfma_f32_16x16x32_bf16 v[10:13], v[140:143], v[238:241], v[10:13]
	v_mfma_f32_16x16x32_bf16 v[2:5], v[148:151], v[238:241], v[2:5]
	v_mfma_f32_16x16x32_bf16 v[58:61], v[144:147], v[218:221], v[58:61]
	v_mfma_f32_16x16x32_bf16 v[50:53], v[152:155], v[218:221], v[50:53]
	v_mfma_f32_16x16x32_bf16 v[42:45], v[144:147], v[226:229], v[42:45]
	v_mfma_f32_16x16x32_bf16 v[34:37], v[152:155], v[226:229], v[34:37]
	v_mfma_f32_16x16x32_bf16 v[26:29], v[144:147], v[234:237], v[26:29]
	v_mfma_f32_16x16x32_bf16 v[18:21], v[152:155], v[234:237], v[18:21]
	v_mfma_f32_16x16x32_bf16 v[10:13], v[144:147], v[242:245], v[10:13]
	v_mfma_f32_16x16x32_bf16 v[2:5], v[152:155], v[242:245], v[2:5]
	s_setprio 0
	s_setprio 1
	v_mfma_f32_16x16x32_bf16 v[62:65], v[182:185], v[214:217], v[62:65]
	v_mfma_f32_16x16x32_bf16 v[54:57], v[190:193], v[214:217], v[54:57]
	v_mfma_f32_16x16x32_bf16 v[46:49], v[182:185], v[222:225], v[46:49]
	v_mfma_f32_16x16x32_bf16 v[38:41], v[190:193], v[222:225], v[38:41]
	v_mfma_f32_16x16x32_bf16 v[30:33], v[182:185], v[230:233], v[30:33]
	v_mfma_f32_16x16x32_bf16 v[22:25], v[190:193], v[230:233], v[22:25]
	v_mfma_f32_16x16x32_bf16 v[14:17], v[182:185], v[238:241], v[14:17]
	v_mfma_f32_16x16x32_bf16 v[6:9], v[190:193], v[238:241], v[6:9]
	v_mfma_f32_16x16x32_bf16 v[62:65], v[186:189], v[218:221], v[62:65]
	v_mfma_f32_16x16x32_bf16 v[54:57], v[210:213], v[218:221], v[54:57]
	v_mfma_f32_16x16x32_bf16 v[46:49], v[186:189], v[226:229], v[46:49]
	v_mfma_f32_16x16x32_bf16 v[38:41], v[210:213], v[226:229], v[38:41]
	v_mfma_f32_16x16x32_bf16 v[30:33], v[186:189], v[234:237], v[30:33]
	v_mfma_f32_16x16x32_bf16 v[22:25], v[210:213], v[234:237], v[22:25]
	v_mfma_f32_16x16x32_bf16 v[14:17], v[186:189], v[242:245], v[14:17]
	v_mfma_f32_16x16x32_bf16 v[6:9], v[210:213], v[242:245], v[6:9]
	s_setprio 0
	s_barrier
	v_add_u32_e32 v130, 0x18000, v138
	ds_read_b128 v[140:143], v130
	ds_read_b128 v[144:147], v130 offset:1024
	ds_read_b128 v[148:151], v130 offset:2048
	ds_read_b128 v[152:155], v130 offset:3072
	v_add_u32_e32 v130, 0x1c000, v138
	ds_read_b128 v[182:185], v130
	ds_read_b128 v[186:189], v130 offset:1024
	ds_read_b128 v[190:193], v130 offset:2048
	ds_read_b128 v[210:213], v130 offset:3072
	ds_read_b128 v[214:217], v139 offset:32768
	ds_read_b128 v[218:221], v139 offset:33792
	ds_read_b128 v[222:225], v139 offset:34816
	ds_read_b128 v[226:229], v139 offset:35840
	ds_read_b128 v[230:233], v139 offset:36864
	ds_read_b128 v[234:237], v139 offset:37888
	ds_read_b128 v[238:241], v139 offset:38912
	ds_read_b128 v[242:245], v139 offset:39936
	s_add_u32 s8, s48, 0x40000
	s_addc_u32 s9, s49, 0
	s_mov_b32 m0, s57
	s_nop 0
	global_load_lds_dwordx4 v0, s[8:9]
	s_nop 0
	s_mov_b32 m0, s58
	s_nop 0
	global_load_lds_dwordx4 v133, s[8:9]
	s_cmp_lg_u32 s18, 0
	s_cbranch_scc1 .Lrx_skip_29
	s_waitcnt vmcnt(8)
.Lrx_skip_29:
	s_waitcnt vmcnt(16)
	s_waitcnt lgkmcnt(0)
	s_barrier
	s_setprio 1
	v_mfma_f32_16x16x32_bf16 v[122:125], v[140:143], v[214:217], v[122:125]
	v_mfma_f32_16x16x32_bf16 v[114:117], v[148:151], v[214:217], v[114:117]
	v_mfma_f32_16x16x32_bf16 v[106:109], v[140:143], v[222:225], v[106:109]
	v_mfma_f32_16x16x32_bf16 v[98:101], v[148:151], v[222:225], v[98:101]
	v_mfma_f32_16x16x32_bf16 v[90:93], v[140:143], v[230:233], v[90:93]
	v_mfma_f32_16x16x32_bf16 v[82:85], v[148:151], v[230:233], v[82:85]
	v_mfma_f32_16x16x32_bf16 v[74:77], v[140:143], v[238:241], v[74:77]
	v_mfma_f32_16x16x32_bf16 v[66:69], v[148:151], v[238:241], v[66:69]
	v_mfma_f32_16x16x32_bf16 v[122:125], v[144:147], v[218:221], v[122:125]
	v_mfma_f32_16x16x32_bf16 v[114:117], v[152:155], v[218:221], v[114:117]
	v_mfma_f32_16x16x32_bf16 v[106:109], v[144:147], v[226:229], v[106:109]
	v_mfma_f32_16x16x32_bf16 v[98:101], v[152:155], v[226:229], v[98:101]
	v_mfma_f32_16x16x32_bf16 v[90:93], v[144:147], v[234:237], v[90:93]
	v_mfma_f32_16x16x32_bf16 v[82:85], v[152:155], v[234:237], v[82:85]
	v_mfma_f32_16x16x32_bf16 v[74:77], v[144:147], v[242:245], v[74:77]
	v_mfma_f32_16x16x32_bf16 v[66:69], v[152:155], v[242:245], v[66:69]
	s_setprio 0
	s_setprio 1
	v_mfma_f32_16x16x32_bf16 v[126:129], v[182:185], v[214:217], v[126:129]
	v_mfma_f32_16x16x32_bf16 v[118:121], v[190:193], v[214:217], v[118:121]
	v_mfma_f32_16x16x32_bf16 v[110:113], v[182:185], v[222:225], v[110:113]
	v_mfma_f32_16x16x32_bf16 v[102:105], v[190:193], v[222:225], v[102:105]
	v_mfma_f32_16x16x32_bf16 v[94:97], v[182:185], v[230:233], v[94:97]
	v_mfma_f32_16x16x32_bf16 v[86:89], v[190:193], v[230:233], v[86:89]
	v_mfma_f32_16x16x32_bf16 v[78:81], v[182:185], v[238:241], v[78:81]
	v_mfma_f32_16x16x32_bf16 v[70:73], v[190:193], v[238:241], v[70:73]
	v_mfma_f32_16x16x32_bf16 v[126:129], v[186:189], v[218:221], v[126:129]
	v_mfma_f32_16x16x32_bf16 v[118:121], v[210:213], v[218:221], v[118:121]
	v_mfma_f32_16x16x32_bf16 v[110:113], v[186:189], v[226:229], v[110:113]
	v_mfma_f32_16x16x32_bf16 v[102:105], v[210:213], v[226:229], v[102:105]
	v_mfma_f32_16x16x32_bf16 v[94:97], v[186:189], v[234:237], v[94:97]
	v_mfma_f32_16x16x32_bf16 v[86:89], v[210:213], v[234:237], v[86:89]
	v_mfma_f32_16x16x32_bf16 v[78:81], v[186:189], v[242:245], v[78:81]
	v_mfma_f32_16x16x32_bf16 v[70:73], v[210:213], v[242:245], v[70:73]
	s_setprio 0
	s_barrier
	ds_read_b128 v[214:217], v139 offset:49152
	ds_read_b128 v[218:221], v139 offset:50176
	ds_read_b128 v[222:225], v139 offset:51200
	ds_read_b128 v[226:229], v139 offset:52224
	ds_read_b128 v[230:233], v139 offset:53248
	ds_read_b128 v[234:237], v139 offset:54272
	ds_read_b128 v[238:241], v139 offset:55296
	ds_read_b128 v[242:245], v139 offset:56320
	s_mov_b32 m0, s59
	s_nop 0
	global_load_lds_dwordx4 v132, s[46:47]
	s_add_u32 s8, s44, 0x40080
	s_mov_b32 m0, s60
	s_nop 0
	global_load_lds_dwordx4 v134, s[46:47]
	s_addc_u32 s9, s45, 0
	s_mov_b32 m0, s63
	s_nop 0
	global_load_lds_dwordx4 v132, s[8:9]
	s_nop 0
	s_mov_b32 m0, s64
	s_nop 0
	global_load_lds_dwordx4 v134, s[8:9]
	s_nop 0
	s_mov_b32 m0, s61
	s_nop 0
	global_load_lds_dwordx4 v0, s[40:41]
	s_nop 0
	s_mov_b32 m0, s62
	s_nop 0
	global_load_lds_dwordx4 v133, s[40:41]
	s_waitcnt vmcnt(8)
	s_waitcnt lgkmcnt(0)
	s_barrier
	s_setprio 1
	v_mfma_f32_16x16x32_bf16 v[58:61], v[140:143], v[214:217], v[58:61]
	v_mfma_f32_16x16x32_bf16 v[50:53], v[148:151], v[214:217], v[50:53]
	v_mfma_f32_16x16x32_bf16 v[42:45], v[140:143], v[222:225], v[42:45]
	v_mfma_f32_16x16x32_bf16 v[34:37], v[148:151], v[222:225], v[34:37]
	v_mfma_f32_16x16x32_bf16 v[26:29], v[140:143], v[230:233], v[26:29]
	v_mfma_f32_16x16x32_bf16 v[18:21], v[148:151], v[230:233], v[18:21]
	v_mfma_f32_16x16x32_bf16 v[10:13], v[140:143], v[238:241], v[10:13]
	v_mfma_f32_16x16x32_bf16 v[2:5], v[148:151], v[238:241], v[2:5]
	v_mfma_f32_16x16x32_bf16 v[58:61], v[144:147], v[218:221], v[58:61]
	v_mfma_f32_16x16x32_bf16 v[50:53], v[152:155], v[218:221], v[50:53]
	v_mfma_f32_16x16x32_bf16 v[42:45], v[144:147], v[226:229], v[42:45]
	v_mfma_f32_16x16x32_bf16 v[34:37], v[152:155], v[226:229], v[34:37]
	v_mfma_f32_16x16x32_bf16 v[26:29], v[144:147], v[234:237], v[26:29]
	v_mfma_f32_16x16x32_bf16 v[18:21], v[152:155], v[234:237], v[18:21]
	v_mfma_f32_16x16x32_bf16 v[10:13], v[144:147], v[242:245], v[10:13]
	v_mfma_f32_16x16x32_bf16 v[2:5], v[152:155], v[242:245], v[2:5]
	s_setprio 0
	s_setprio 1
	v_mfma_f32_16x16x32_bf16 v[62:65], v[182:185], v[214:217], v[62:65]
	v_mfma_f32_16x16x32_bf16 v[54:57], v[190:193], v[214:217], v[54:57]
	v_mfma_f32_16x16x32_bf16 v[46:49], v[182:185], v[222:225], v[46:49]
	v_mfma_f32_16x16x32_bf16 v[38:41], v[190:193], v[222:225], v[38:41]
	v_mfma_f32_16x16x32_bf16 v[30:33], v[182:185], v[230:233], v[30:33]
	v_mfma_f32_16x16x32_bf16 v[22:25], v[190:193], v[230:233], v[22:25]
	v_mfma_f32_16x16x32_bf16 v[14:17], v[182:185], v[238:241], v[14:17]
	v_mfma_f32_16x16x32_bf16 v[6:9], v[190:193], v[238:241], v[6:9]
	v_mfma_f32_16x16x32_bf16 v[62:65], v[186:189], v[218:221], v[62:65]
	v_mfma_f32_16x16x32_bf16 v[54:57], v[210:213], v[218:221], v[54:57]
	v_mfma_f32_16x16x32_bf16 v[46:49], v[186:189], v[226:229], v[46:49]
	v_mfma_f32_16x16x32_bf16 v[38:41], v[210:213], v[226:229], v[38:41]
	v_mfma_f32_16x16x32_bf16 v[30:33], v[186:189], v[234:237], v[30:33]
	v_mfma_f32_16x16x32_bf16 v[22:25], v[210:213], v[234:237], v[22:25]
	v_mfma_f32_16x16x32_bf16 v[14:17], v[186:189], v[242:245], v[14:17]
	v_mfma_f32_16x16x32_bf16 v[6:9], v[210:213], v[242:245], v[6:9]
	s_setprio 0
	s_barrier
	s_add_i32 s74, s74, 2
	s_add_u32 s31, s31, 0x100
	s_addc_u32 s72, s72, 0
	s_add_u32 s38, s38, 0x100
	s_addc_u32 s39, s39, 0
	s_cmp_gt_u32 s74, 13
	s_cbranch_scc0 .LBB0_606
	s_and_b64 vcc, exec, s[20:21]
	s_cbranch_vccz .LBB0_609
	s_barrier
